# v122 stack with the per-segment s_setprio toggles removed from the 7 GEMM K-loops (priority lever: toggling does not pay)
# speedup vs baseline: 1.0021x; 1.0021x over previous
.LBB0_58:
	s_add_u32 s0, s56, 0xfffc0080
	s_addc_u32 s1, s57, -1
	s_add_i32 s22, 0, 0x10000
	s_cmp_eq_u32 s64, 12
	s_cselect_b32 s61, s20, s1
	s_cselect_b32 s60, s21, s0
	s_cselect_b32 s59, s51, s63
	s_cselect_b32 s58, s55, s62
	s_add_i32 s37, 0, 0x14000
	v_add_u32_e32 v156, s22, v142
	v_add_u32_e32 v172, s37, v142
	ds_read_b128 v[144:147], v156
	ds_read_b128 v[148:151], v156 offset:1024
	ds_read_b128 v[152:155], v156 offset:2048
	ds_read_b128 v[156:159], v156 offset:3072
	ds_read_b128 v[160:163], v172
	ds_read_b128 v[164:167], v172 offset:1024
	ds_read_b128 v[168:171], v172 offset:2048
	ds_read_b128 v[172:175], v172 offset:3072
	v_lshl_add_u64 v[228:229], s[56:57], 0, v[138:139]
	s_add_i32 m0, s66, 0xc000
	ds_read_b128 v[178:181], v143
	ds_read_b128 v[182:185], v143 offset:1024
	ds_read_b128 v[186:189], v143 offset:2048
	ds_read_b128 v[208:211], v143 offset:3072
	ds_read_b128 v[212:215], v143 offset:4096
	ds_read_b128 v[216:219], v143 offset:5120
	ds_read_b128 v[220:223], v143 offset:6144
	ds_read_b128 v[224:227], v143 offset:7168
	global_load_lds_dwordx4 v[228:229], off
	v_lshl_add_u64 v[228:229], s[56:57], 0, v[140:141]
	s_add_i32 m0, s66, 0xe000
	s_nop 0
	global_load_lds_dwordx4 v[228:229], off
	s_waitcnt vmcnt(8)
	s_waitcnt lgkmcnt(0)
	s_barrier
	s_waitcnt lgkmcnt(0)
	v_mfma_f32_16x16x32_bf16 v[124:127], v[144:147], v[178:181], v[124:127]
	v_mfma_f32_16x16x32_bf16 v[116:119], v[152:155], v[178:181], v[116:119]
	v_mfma_f32_16x16x32_bf16 v[108:111], v[144:147], v[186:189], v[108:111]
	v_mfma_f32_16x16x32_bf16 v[100:103], v[152:155], v[186:189], v[100:103]
	v_mfma_f32_16x16x32_bf16 v[92:95], v[144:147], v[212:215], v[92:95]
	v_mfma_f32_16x16x32_bf16 v[84:87], v[152:155], v[212:215], v[84:87]
	v_mfma_f32_16x16x32_bf16 v[76:79], v[144:147], v[220:223], v[76:79]
	v_mfma_f32_16x16x32_bf16 v[68:71], v[152:155], v[220:223], v[68:71]
	v_mfma_f32_16x16x32_bf16 v[124:127], v[148:151], v[182:185], v[124:127]
	v_mfma_f32_16x16x32_bf16 v[116:119], v[156:159], v[182:185], v[116:119]
	v_mfma_f32_16x16x32_bf16 v[108:111], v[148:151], v[208:211], v[108:111]
	v_mfma_f32_16x16x32_bf16 v[100:103], v[156:159], v[208:211], v[100:103]
	v_mfma_f32_16x16x32_bf16 v[92:95], v[148:151], v[216:219], v[92:95]
	v_mfma_f32_16x16x32_bf16 v[84:87], v[156:159], v[216:219], v[84:87]
	v_mfma_f32_16x16x32_bf16 v[76:79], v[148:151], v[224:227], v[76:79]
	v_mfma_f32_16x16x32_bf16 v[68:71], v[156:159], v[224:227], v[68:71]
	v_mfma_f32_16x16x32_bf16 v[120:123], v[160:163], v[178:181], v[120:123]
	v_mfma_f32_16x16x32_bf16 v[112:115], v[168:171], v[178:181], v[112:115]
	v_mfma_f32_16x16x32_bf16 v[104:107], v[160:163], v[186:189], v[104:107]
	v_mfma_f32_16x16x32_bf16 v[96:99], v[168:171], v[186:189], v[96:99]
	v_mfma_f32_16x16x32_bf16 v[88:91], v[160:163], v[212:215], v[88:91]
	v_mfma_f32_16x16x32_bf16 v[80:83], v[168:171], v[212:215], v[80:83]
	v_mfma_f32_16x16x32_bf16 v[72:75], v[160:163], v[220:223], v[72:75]
	v_mfma_f32_16x16x32_bf16 v[64:67], v[168:171], v[220:223], v[64:67]
	v_mfma_f32_16x16x32_bf16 v[120:123], v[164:167], v[182:185], v[120:123]
	v_mfma_f32_16x16x32_bf16 v[112:115], v[172:175], v[182:185], v[112:115]
	v_mfma_f32_16x16x32_bf16 v[104:107], v[164:167], v[208:211], v[104:107]
	v_mfma_f32_16x16x32_bf16 v[96:99], v[172:175], v[208:211], v[96:99]
	v_mfma_f32_16x16x32_bf16 v[88:91], v[164:167], v[216:219], v[88:91]
	v_mfma_f32_16x16x32_bf16 v[80:83], v[172:175], v[216:219], v[80:83]
	v_mfma_f32_16x16x32_bf16 v[72:75], v[164:167], v[224:227], v[72:75]
	v_mfma_f32_16x16x32_bf16 v[64:67], v[172:175], v[224:227], v[64:67]
	s_barrier
	s_add_i32 s0, s22, s35
	v_lshl_add_u64 v[228:229], s[58:59], 0, v[132:133]
	s_mov_b32 m0, s0
	ds_read_b128 v[178:181], v143 offset:16384
	ds_read_b128 v[182:185], v143 offset:17408
	ds_read_b128 v[186:189], v143 offset:18432
	ds_read_b128 v[208:211], v143 offset:19456
	ds_read_b128 v[212:215], v143 offset:20480
	ds_read_b128 v[216:219], v143 offset:21504
	ds_read_b128 v[220:223], v143 offset:22528
	ds_read_b128 v[224:227], v143 offset:23552
	global_load_lds_dwordx4 v[228:229], off
	s_add_i32 m0, s0, 0x2000
	s_add_u32 s0, s58, 0x10000
	v_lshl_add_u64 v[230:231], s[58:59], 0, v[128:129]
	s_addc_u32 s1, s59, 0
	s_add_i32 s22, s37, s35
	global_load_lds_dwordx4 v[230:231], off
	v_lshl_add_u64 v[232:233], s[0:1], 0, v[132:133]
	s_mov_b32 m0, s22
	v_lshl_add_u64 v[234:235], s[60:61], 0, v[130:131]
	global_load_lds_dwordx4 v[232:233], off
	v_lshl_add_u64 v[232:233], s[0:1], 0, v[128:129]
	s_add_i32 m0, s22, 0x2000
	s_nop 0
	global_load_lds_dwordx4 v[232:233], off
	v_lshl_add_u64 v[232:233], s[60:61], 0, v[134:135]
	s_mov_b32 m0, s66
	s_nop 0
	global_load_lds_dwordx4 v[232:233], off
	s_mov_b32 m0, s67
	s_nop 0
	global_load_lds_dwordx4 v[234:235], off
	s_waitcnt vmcnt(8)
	s_waitcnt lgkmcnt(0)
	s_barrier
	s_waitcnt lgkmcnt(0)
	v_mfma_f32_16x16x32_bf16 v[60:63], v[144:147], v[178:181], v[60:63]
	v_mfma_f32_16x16x32_bf16 v[52:55], v[152:155], v[178:181], v[52:55]
	v_mfma_f32_16x16x32_bf16 v[44:47], v[144:147], v[186:189], v[44:47]
	v_mfma_f32_16x16x32_bf16 v[36:39], v[152:155], v[186:189], v[36:39]
	v_mfma_f32_16x16x32_bf16 v[28:31], v[144:147], v[212:215], v[28:31]
	v_mfma_f32_16x16x32_bf16 v[20:23], v[152:155], v[212:215], v[20:23]
	v_mfma_f32_16x16x32_bf16 v[12:15], v[144:147], v[220:223], v[12:15]
	v_mfma_f32_16x16x32_bf16 v[4:7], v[152:155], v[220:223], v[4:7]
	v_mfma_f32_16x16x32_bf16 v[60:63], v[148:151], v[182:185], v[60:63]
	v_mfma_f32_16x16x32_bf16 v[52:55], v[156:159], v[182:185], v[52:55]
	v_mfma_f32_16x16x32_bf16 v[44:47], v[148:151], v[208:211], v[44:47]
	v_mfma_f32_16x16x32_bf16 v[36:39], v[156:159], v[208:211], v[36:39]
	v_mfma_f32_16x16x32_bf16 v[28:31], v[148:151], v[216:219], v[28:31]
	v_mfma_f32_16x16x32_bf16 v[20:23], v[156:159], v[216:219], v[20:23]
	v_mfma_f32_16x16x32_bf16 v[12:15], v[148:151], v[224:227], v[12:15]
	v_mfma_f32_16x16x32_bf16 v[4:7], v[156:159], v[224:227], v[4:7]
	v_mfma_f32_16x16x32_bf16 v[56:59], v[160:163], v[178:181], v[56:59]
	v_mfma_f32_16x16x32_bf16 v[48:51], v[168:171], v[178:181], v[48:51]
	v_mfma_f32_16x16x32_bf16 v[40:43], v[160:163], v[186:189], v[40:43]
	v_mfma_f32_16x16x32_bf16 v[32:35], v[168:171], v[186:189], v[32:35]
	v_mfma_f32_16x16x32_bf16 v[24:27], v[160:163], v[212:215], v[24:27]
	v_mfma_f32_16x16x32_bf16 v[16:19], v[168:171], v[212:215], v[16:19]
	v_mfma_f32_16x16x32_bf16 v[8:11], v[160:163], v[220:223], v[8:11]
	v_mfma_f32_16x16x32_bf16 v[0:3], v[168:171], v[220:223], v[0:3]
	v_mfma_f32_16x16x32_bf16 v[56:59], v[164:167], v[182:185], v[56:59]
	v_mfma_f32_16x16x32_bf16 v[48:51], v[172:175], v[182:185], v[48:51]
	v_mfma_f32_16x16x32_bf16 v[40:43], v[164:167], v[208:211], v[40:43]
	v_mfma_f32_16x16x32_bf16 v[32:35], v[172:175], v[208:211], v[32:35]
	v_mfma_f32_16x16x32_bf16 v[24:27], v[164:167], v[216:219], v[24:27]
	v_mfma_f32_16x16x32_bf16 v[16:19], v[172:175], v[216:219], v[16:19]
	v_mfma_f32_16x16x32_bf16 v[8:11], v[164:167], v[224:227], v[8:11]
	v_mfma_f32_16x16x32_bf16 v[0:3], v[172:175], v[224:227], v[0:3]
	s_barrier
	s_add_i32 s22, 0, 0x18000
	s_add_i32 s37, 0, 0x1c000
	v_add_u32_e32 v156, s22, v142
	v_add_u32_e32 v172, s37, v142
	ds_read_b128 v[144:147], v156
	ds_read_b128 v[148:151], v156 offset:1024
	ds_read_b128 v[152:155], v156 offset:2048
	ds_read_b128 v[156:159], v156 offset:3072
	ds_read_b128 v[160:163], v172
	ds_read_b128 v[164:167], v172 offset:1024
	ds_read_b128 v[168:171], v172 offset:2048
	ds_read_b128 v[172:175], v172 offset:3072
	s_add_u32 s0, s60, 0x40000
	s_addc_u32 s1, s61, 0
	s_mov_b32 m0, s68
	v_lshl_add_u64 v[236:237], s[0:1], 0, v[134:135]
	ds_read_b128 v[178:181], v143 offset:32768
	ds_read_b128 v[182:185], v143 offset:33792
	ds_read_b128 v[186:189], v143 offset:34816
	ds_read_b128 v[208:211], v143 offset:35840
	ds_read_b128 v[212:215], v143 offset:36864
	ds_read_b128 v[216:219], v143 offset:37888
	ds_read_b128 v[220:223], v143 offset:38912
	ds_read_b128 v[224:227], v143 offset:39936
	global_load_lds_dwordx4 v[236:237], off
	v_lshl_add_u64 v[236:237], s[0:1], 0, v[130:131]
	s_mov_b32 m0, s69
	s_nop 0
	global_load_lds_dwordx4 v[236:237], off
	s_waitcnt vmcnt(8)
	s_waitcnt lgkmcnt(0)
	s_barrier
	s_waitcnt lgkmcnt(0)
	v_mfma_f32_16x16x32_bf16 v[124:127], v[144:147], v[178:181], v[124:127]
	v_mfma_f32_16x16x32_bf16 v[116:119], v[152:155], v[178:181], v[116:119]
	v_mfma_f32_16x16x32_bf16 v[108:111], v[144:147], v[186:189], v[108:111]
	v_mfma_f32_16x16x32_bf16 v[100:103], v[152:155], v[186:189], v[100:103]
	v_mfma_f32_16x16x32_bf16 v[92:95], v[144:147], v[212:215], v[92:95]
	v_mfma_f32_16x16x32_bf16 v[84:87], v[152:155], v[212:215], v[84:87]
	v_mfma_f32_16x16x32_bf16 v[76:79], v[144:147], v[220:223], v[76:79]
	v_mfma_f32_16x16x32_bf16 v[68:71], v[152:155], v[220:223], v[68:71]
	v_mfma_f32_16x16x32_bf16 v[124:127], v[148:151], v[182:185], v[124:127]
	v_mfma_f32_16x16x32_bf16 v[116:119], v[156:159], v[182:185], v[116:119]
	v_mfma_f32_16x16x32_bf16 v[108:111], v[148:151], v[208:211], v[108:111]
	v_mfma_f32_16x16x32_bf16 v[100:103], v[156:159], v[208:211], v[100:103]
	v_mfma_f32_16x16x32_bf16 v[92:95], v[148:151], v[216:219], v[92:95]
	v_mfma_f32_16x16x32_bf16 v[84:87], v[156:159], v[216:219], v[84:87]
	v_mfma_f32_16x16x32_bf16 v[76:79], v[148:151], v[224:227], v[76:79]
	v_mfma_f32_16x16x32_bf16 v[68:71], v[156:159], v[224:227], v[68:71]
	v_mfma_f32_16x16x32_bf16 v[120:123], v[160:163], v[178:181], v[120:123]
	v_mfma_f32_16x16x32_bf16 v[112:115], v[168:171], v[178:181], v[112:115]
	v_mfma_f32_16x16x32_bf16 v[104:107], v[160:163], v[186:189], v[104:107]
	v_mfma_f32_16x16x32_bf16 v[96:99], v[168:171], v[186:189], v[96:99]
	v_mfma_f32_16x16x32_bf16 v[88:91], v[160:163], v[212:215], v[88:91]
	v_mfma_f32_16x16x32_bf16 v[80:83], v[168:171], v[212:215], v[80:83]
	v_mfma_f32_16x16x32_bf16 v[72:75], v[160:163], v[220:223], v[72:75]
	v_mfma_f32_16x16x32_bf16 v[64:67], v[168:171], v[220:223], v[64:67]
	v_mfma_f32_16x16x32_bf16 v[120:123], v[164:167], v[182:185], v[120:123]
	v_mfma_f32_16x16x32_bf16 v[112:115], v[172:175], v[182:185], v[112:115]
	v_mfma_f32_16x16x32_bf16 v[104:107], v[164:167], v[208:211], v[104:107]
	v_mfma_f32_16x16x32_bf16 v[96:99], v[172:175], v[208:211], v[96:99]
	v_mfma_f32_16x16x32_bf16 v[88:91], v[164:167], v[216:219], v[88:91]
	v_mfma_f32_16x16x32_bf16 v[80:83], v[172:175], v[216:219], v[80:83]
	v_mfma_f32_16x16x32_bf16 v[72:75], v[164:167], v[224:227], v[72:75]
	v_mfma_f32_16x16x32_bf16 v[64:67], v[172:175], v[224:227], v[64:67]
	s_barrier
	s_add_i32 s0, s22, s35
	v_lshl_add_u64 v[228:229], v[228:229], 0, s[26:27]
	s_mov_b32 m0, s0
	ds_read_b128 v[178:181], v143 offset:49152
	ds_read_b128 v[182:185], v143 offset:50176
	ds_read_b128 v[186:189], v143 offset:51200
	ds_read_b128 v[208:211], v143 offset:52224
	ds_read_b128 v[212:215], v143 offset:53248
	ds_read_b128 v[216:219], v143 offset:54272
	ds_read_b128 v[220:223], v143 offset:55296
	ds_read_b128 v[224:227], v143 offset:56320
	global_load_lds_dwordx4 v[228:229], off
	s_add_i32 m0, s0, 0x2000
	s_add_u32 s0, s58, 0x10080
	v_lshl_add_u64 v[228:229], v[230:231], 0, s[26:27]
	s_addc_u32 s1, s59, 0
	s_add_i32 s22, s37, s35
	global_load_lds_dwordx4 v[228:229], off
	v_lshl_add_u64 v[228:229], s[0:1], 0, v[132:133]
	s_mov_b32 m0, s22
	s_nop 0
	global_load_lds_dwordx4 v[228:229], off
	v_lshl_add_u64 v[228:229], s[0:1], 0, v[128:129]
	s_add_i32 m0, s22, 0x2000
	s_nop 0
	global_load_lds_dwordx4 v[228:229], off
	v_lshl_add_u64 v[228:229], v[232:233], 0, s[26:27]
	s_mov_b32 m0, s48
	s_nop 0
	global_load_lds_dwordx4 v[228:229], off
	v_lshl_add_u64 v[228:229], v[234:235], 0, s[26:27]
	s_mov_b32 m0, s49
	s_nop 0
	global_load_lds_dwordx4 v[228:229], off
	s_waitcnt vmcnt(8)
	s_waitcnt lgkmcnt(0)
	s_barrier
	s_waitcnt lgkmcnt(0)
	v_mfma_f32_16x16x32_bf16 v[60:63], v[144:147], v[178:181], v[60:63]
	v_mfma_f32_16x16x32_bf16 v[52:55], v[152:155], v[178:181], v[52:55]
	v_mfma_f32_16x16x32_bf16 v[44:47], v[144:147], v[186:189], v[44:47]
	v_mfma_f32_16x16x32_bf16 v[36:39], v[152:155], v[186:189], v[36:39]
	v_mfma_f32_16x16x32_bf16 v[28:31], v[144:147], v[212:215], v[28:31]
	v_mfma_f32_16x16x32_bf16 v[20:23], v[152:155], v[212:215], v[20:23]
	v_mfma_f32_16x16x32_bf16 v[12:15], v[144:147], v[220:223], v[12:15]
	v_mfma_f32_16x16x32_bf16 v[4:7], v[152:155], v[220:223], v[4:7]
	v_mfma_f32_16x16x32_bf16 v[60:63], v[148:151], v[182:185], v[60:63]
	v_mfma_f32_16x16x32_bf16 v[52:55], v[156:159], v[182:185], v[52:55]
	v_mfma_f32_16x16x32_bf16 v[44:47], v[148:151], v[208:211], v[44:47]
	v_mfma_f32_16x16x32_bf16 v[36:39], v[156:159], v[208:211], v[36:39]
	v_mfma_f32_16x16x32_bf16 v[28:31], v[148:151], v[216:219], v[28:31]
	v_mfma_f32_16x16x32_bf16 v[20:23], v[156:159], v[216:219], v[20:23]
	v_mfma_f32_16x16x32_bf16 v[12:15], v[148:151], v[224:227], v[12:15]
	v_mfma_f32_16x16x32_bf16 v[4:7], v[156:159], v[224:227], v[4:7]
	v_mfma_f32_16x16x32_bf16 v[56:59], v[160:163], v[178:181], v[56:59]
	v_mfma_f32_16x16x32_bf16 v[48:51], v[168:171], v[178:181], v[48:51]
	v_mfma_f32_16x16x32_bf16 v[40:43], v[160:163], v[186:189], v[40:43]
	v_mfma_f32_16x16x32_bf16 v[32:35], v[168:171], v[186:189], v[32:35]
	v_mfma_f32_16x16x32_bf16 v[24:27], v[160:163], v[212:215], v[24:27]
	v_mfma_f32_16x16x32_bf16 v[16:19], v[168:171], v[212:215], v[16:19]
	v_mfma_f32_16x16x32_bf16 v[8:11], v[160:163], v[220:223], v[8:11]
	v_mfma_f32_16x16x32_bf16 v[0:3], v[168:171], v[220:223], v[0:3]
	v_mfma_f32_16x16x32_bf16 v[56:59], v[164:167], v[182:185], v[56:59]
	v_mfma_f32_16x16x32_bf16 v[48:51], v[172:175], v[182:185], v[48:51]
	v_mfma_f32_16x16x32_bf16 v[40:43], v[164:167], v[208:211], v[40:43]
	v_mfma_f32_16x16x32_bf16 v[32:35], v[172:175], v[208:211], v[32:35]
	v_mfma_f32_16x16x32_bf16 v[24:27], v[164:167], v[216:219], v[24:27]
	v_mfma_f32_16x16x32_bf16 v[16:19], v[172:175], v[216:219], v[16:19]
	v_mfma_f32_16x16x32_bf16 v[8:11], v[164:167], v[224:227], v[8:11]
	v_mfma_f32_16x16x32_bf16 v[0:3], v[172:175], v[224:227], v[0:3]
	s_barrier
	s_add_i32 s64, s64, 2
	s_add_u32 s56, s56, 0x100
	s_addc_u32 s57, s57, 0
	s_add_u32 s62, s62, 0x100
	s_addc_u32 s63, s63, 0
	s_cmp_gt_u32 s64, 13
	s_cbranch_scc0 .LBB0_58
	v_readlane_b32 s0, v252, 28
	v_readlane_b32 s1, v252, 29
	s_and_b64 vcc, exec, s[0:1]
	s_cbranch_vccz .LBB0_61
	s_barrier

.LBB0_116:
	s_add_u32 s0, s56, 0xfffc0080
	s_addc_u32 s37, s57, -1
	s_add_i32 s39, 0, 0x10000
	s_cmp_eq_u32 s70, 12
	s_cselect_b32 s61, s20, s37
	s_cselect_b32 s60, s21, s0
	s_cselect_b32 s59, s62, s65
	s_cselect_b32 s58, s63, s64
	s_add_i32 s0, 0, 0x14000
	v_add_u32_e32 v168, s39, v180
	v_add_u32_e32 v178, s0, v180
	ds_read_b128 v[128:131], v168
	ds_read_b128 v[132:135], v168 offset:1024
	ds_read_b128 v[164:167], v168 offset:2048
	ds_read_b128 v[168:171], v168 offset:3072
	ds_read_b128 v[172:175], v178
	ds_read_b128 v[182:185], v178 offset:1024
	ds_read_b128 v[186:189], v178 offset:2048
	ds_read_b128 v[208:211], v178 offset:3072
	v_lshl_add_u64 v[178:179], s[56:57], 0, v[160:161]
	s_add_i32 m0, s66, 0xc000
	ds_read_b128 v[212:215], v181
	ds_read_b128 v[216:219], v181 offset:1024
	ds_read_b128 v[220:223], v181 offset:2048
	ds_read_b128 v[224:227], v181 offset:3072
	ds_read_b128 v[228:231], v181 offset:4096
	ds_read_b128 v[232:235], v181 offset:5120
	ds_read_b128 v[236:239], v181 offset:6144
	ds_read_b128 v[240:243], v181 offset:7168
	global_load_lds_dwordx4 v[178:179], off
	v_lshl_add_u64 v[178:179], s[56:57], 0, v[162:163]
	s_add_i32 m0, s66, 0xe000
	s_nop 0
	global_load_lds_dwordx4 v[178:179], off
	s_waitcnt vmcnt(8)
	s_waitcnt lgkmcnt(0)
	s_barrier
	s_waitcnt lgkmcnt(0)
	v_mfma_f32_16x16x32_bf16 v[124:127], v[128:131], v[212:215], v[124:127]
	v_mfma_f32_16x16x32_bf16 v[120:123], v[164:167], v[212:215], v[120:123]
	v_mfma_f32_16x16x32_bf16 v[116:119], v[128:131], v[220:223], v[116:119]
	v_mfma_f32_16x16x32_bf16 v[112:115], v[164:167], v[220:223], v[112:115]
	v_mfma_f32_16x16x32_bf16 v[108:111], v[128:131], v[228:231], v[108:111]
	v_mfma_f32_16x16x32_bf16 v[104:107], v[164:167], v[228:231], v[104:107]
	v_mfma_f32_16x16x32_bf16 v[100:103], v[128:131], v[236:239], v[100:103]
	v_mfma_f32_16x16x32_bf16 v[96:99], v[164:167], v[236:239], v[96:99]
	v_mfma_f32_16x16x32_bf16 v[124:127], v[132:135], v[216:219], v[124:127]
	v_mfma_f32_16x16x32_bf16 v[120:123], v[168:171], v[216:219], v[120:123]
	v_mfma_f32_16x16x32_bf16 v[116:119], v[132:135], v[224:227], v[116:119]
	v_mfma_f32_16x16x32_bf16 v[112:115], v[168:171], v[224:227], v[112:115]
	v_mfma_f32_16x16x32_bf16 v[108:111], v[132:135], v[232:235], v[108:111]
	v_mfma_f32_16x16x32_bf16 v[104:107], v[168:171], v[232:235], v[104:107]
	v_mfma_f32_16x16x32_bf16 v[100:103], v[132:135], v[240:243], v[100:103]
	v_mfma_f32_16x16x32_bf16 v[96:99], v[168:171], v[240:243], v[96:99]
	v_mfma_f32_16x16x32_bf16 v[60:63], v[172:175], v[212:215], v[60:63]
	v_mfma_f32_16x16x32_bf16 v[56:59], v[186:189], v[212:215], v[56:59]
	v_mfma_f32_16x16x32_bf16 v[52:55], v[172:175], v[220:223], v[52:55]
	v_mfma_f32_16x16x32_bf16 v[48:51], v[186:189], v[220:223], v[48:51]
	v_mfma_f32_16x16x32_bf16 v[44:47], v[172:175], v[228:231], v[44:47]
	v_mfma_f32_16x16x32_bf16 v[40:43], v[186:189], v[228:231], v[40:43]
	v_mfma_f32_16x16x32_bf16 v[36:39], v[172:175], v[236:239], v[36:39]
	v_mfma_f32_16x16x32_bf16 v[32:35], v[186:189], v[236:239], v[32:35]
	v_mfma_f32_16x16x32_bf16 v[60:63], v[182:185], v[216:219], v[60:63]
	v_mfma_f32_16x16x32_bf16 v[56:59], v[208:211], v[216:219], v[56:59]
	v_mfma_f32_16x16x32_bf16 v[52:55], v[182:185], v[224:227], v[52:55]
	v_mfma_f32_16x16x32_bf16 v[48:51], v[208:211], v[224:227], v[48:51]
	v_mfma_f32_16x16x32_bf16 v[44:47], v[182:185], v[232:235], v[44:47]
	v_mfma_f32_16x16x32_bf16 v[40:43], v[208:211], v[232:235], v[40:43]
	v_mfma_f32_16x16x32_bf16 v[36:39], v[182:185], v[240:243], v[36:39]
	v_mfma_f32_16x16x32_bf16 v[32:35], v[208:211], v[240:243], v[32:35]
	s_barrier
	s_add_i32 s37, s39, s35
	v_lshl_add_u64 v[178:179], s[58:59], 0, v[140:141]
	s_mov_b32 m0, s37
	ds_read_b128 v[212:215], v181 offset:16384
	ds_read_b128 v[216:219], v181 offset:17408
	ds_read_b128 v[220:223], v181 offset:18432
	ds_read_b128 v[224:227], v181 offset:19456
	ds_read_b128 v[228:231], v181 offset:20480
	ds_read_b128 v[232:235], v181 offset:21504
	ds_read_b128 v[236:239], v181 offset:22528
	ds_read_b128 v[240:243], v181 offset:23552
	global_load_lds_dwordx4 v[178:179], off
	s_add_i32 m0, s37, 0x2000
	s_add_u32 s52, s58, 0x10000
	v_lshl_add_u64 v[244:245], s[58:59], 0, v[136:137]
	s_addc_u32 s53, s59, 0
	s_add_i32 s0, s0, s35
	global_load_lds_dwordx4 v[244:245], off
	v_lshl_add_u64 v[246:247], s[52:53], 0, v[140:141]
	s_mov_b32 m0, s0
	v_lshl_add_u64 v[248:249], s[60:61], 0, v[138:139]
	global_load_lds_dwordx4 v[246:247], off
	v_lshl_add_u64 v[246:247], s[52:53], 0, v[136:137]
	s_add_i32 m0, s0, 0x2000
	s_nop 0
	global_load_lds_dwordx4 v[246:247], off
	v_lshl_add_u64 v[246:247], s[60:61], 0, v[142:143]
	s_mov_b32 m0, s66
	s_nop 0
	global_load_lds_dwordx4 v[246:247], off
	s_mov_b32 m0, s67
	s_nop 0
	global_load_lds_dwordx4 v[248:249], off
	s_waitcnt vmcnt(8)
	s_waitcnt lgkmcnt(0)
	s_barrier
	s_waitcnt lgkmcnt(0)
	v_mfma_f32_16x16x32_bf16 v[92:95], v[128:131], v[212:215], v[92:95]
	v_mfma_f32_16x16x32_bf16 v[88:91], v[164:167], v[212:215], v[88:91]
	v_mfma_f32_16x16x32_bf16 v[84:87], v[128:131], v[220:223], v[84:87]
	v_mfma_f32_16x16x32_bf16 v[80:83], v[164:167], v[220:223], v[80:83]
	v_mfma_f32_16x16x32_bf16 v[76:79], v[128:131], v[228:231], v[76:79]
	v_mfma_f32_16x16x32_bf16 v[72:75], v[164:167], v[228:231], v[72:75]
	v_mfma_f32_16x16x32_bf16 v[68:71], v[128:131], v[236:239], v[68:71]
	v_mfma_f32_16x16x32_bf16 v[64:67], v[164:167], v[236:239], v[64:67]
	v_mfma_f32_16x16x32_bf16 v[92:95], v[132:135], v[216:219], v[92:95]
	v_mfma_f32_16x16x32_bf16 v[88:91], v[168:171], v[216:219], v[88:91]
	v_mfma_f32_16x16x32_bf16 v[84:87], v[132:135], v[224:227], v[84:87]
	v_mfma_f32_16x16x32_bf16 v[80:83], v[168:171], v[224:227], v[80:83]
	v_mfma_f32_16x16x32_bf16 v[76:79], v[132:135], v[232:235], v[76:79]
	v_mfma_f32_16x16x32_bf16 v[72:75], v[168:171], v[232:235], v[72:75]
	v_mfma_f32_16x16x32_bf16 v[68:71], v[132:135], v[240:243], v[68:71]
	v_mfma_f32_16x16x32_bf16 v[64:67], v[168:171], v[240:243], v[64:67]
	v_mfma_f32_16x16x32_bf16 v[28:31], v[172:175], v[212:215], v[28:31]
	v_mfma_f32_16x16x32_bf16 v[24:27], v[186:189], v[212:215], v[24:27]
	v_mfma_f32_16x16x32_bf16 v[20:23], v[172:175], v[220:223], v[20:23]
	v_mfma_f32_16x16x32_bf16 v[16:19], v[186:189], v[220:223], v[16:19]
	v_mfma_f32_16x16x32_bf16 v[12:15], v[172:175], v[228:231], v[12:15]
	v_mfma_f32_16x16x32_bf16 v[8:11], v[186:189], v[228:231], v[8:11]
	v_mfma_f32_16x16x32_bf16 v[4:7], v[172:175], v[236:239], v[4:7]
	v_mfma_f32_16x16x32_bf16 v[0:3], v[186:189], v[236:239], v[0:3]
	v_mfma_f32_16x16x32_bf16 v[28:31], v[182:185], v[216:219], v[28:31]
	v_mfma_f32_16x16x32_bf16 v[24:27], v[208:211], v[216:219], v[24:27]
	v_mfma_f32_16x16x32_bf16 v[20:23], v[182:185], v[224:227], v[20:23]
	v_mfma_f32_16x16x32_bf16 v[16:19], v[208:211], v[224:227], v[16:19]
	v_mfma_f32_16x16x32_bf16 v[12:15], v[182:185], v[232:235], v[12:15]
	v_mfma_f32_16x16x32_bf16 v[8:11], v[208:211], v[232:235], v[8:11]
	v_mfma_f32_16x16x32_bf16 v[4:7], v[182:185], v[240:243], v[4:7]
	v_mfma_f32_16x16x32_bf16 v[0:3], v[208:211], v[240:243], v[0:3]
	s_barrier
	s_add_i32 s0, 0, 0x18000
	s_add_i32 s37, 0, 0x1c000
	v_add_u32_e32 v168, s0, v180
	v_add_u32_e32 v207, s37, v180
	ds_read_b128 v[128:131], v168
	ds_read_b128 v[132:135], v168 offset:1024
	ds_read_b128 v[164:167], v168 offset:2048
	ds_read_b128 v[168:171], v168 offset:3072
	ds_read_b128 v[172:175], v207
	ds_read_b128 v[182:185], v207 offset:1024
	ds_read_b128 v[186:189], v207 offset:2048
	ds_read_b128 v[208:211], v207 offset:3072
	s_add_u32 s52, s60, 0x40000
	s_addc_u32 s53, s61, 0
	s_mov_b32 m0, s68
	v_lshl_add_u64 v[250:251], s[52:53], 0, v[142:143]
	ds_read_b128 v[212:215], v181 offset:32768
	ds_read_b128 v[216:219], v181 offset:33792
	ds_read_b128 v[220:223], v181 offset:34816
	ds_read_b128 v[224:227], v181 offset:35840
	ds_read_b128 v[228:231], v181 offset:36864
	ds_read_b128 v[232:235], v181 offset:37888
	ds_read_b128 v[236:239], v181 offset:38912
	ds_read_b128 v[240:243], v181 offset:39936
	global_load_lds_dwordx4 v[250:251], off
	v_lshl_add_u64 v[250:251], s[52:53], 0, v[138:139]
	s_mov_b32 m0, s69
	s_nop 0
	global_load_lds_dwordx4 v[250:251], off
	s_waitcnt vmcnt(8)
	s_waitcnt lgkmcnt(0)
	s_barrier
	s_waitcnt lgkmcnt(0)
	v_mfma_f32_16x16x32_bf16 v[124:127], v[128:131], v[212:215], v[124:127]
	v_mfma_f32_16x16x32_bf16 v[120:123], v[164:167], v[212:215], v[120:123]
	v_mfma_f32_16x16x32_bf16 v[116:119], v[128:131], v[220:223], v[116:119]
	v_mfma_f32_16x16x32_bf16 v[112:115], v[164:167], v[220:223], v[112:115]
	v_mfma_f32_16x16x32_bf16 v[108:111], v[128:131], v[228:231], v[108:111]
	v_mfma_f32_16x16x32_bf16 v[104:107], v[164:167], v[228:231], v[104:107]
	v_mfma_f32_16x16x32_bf16 v[100:103], v[128:131], v[236:239], v[100:103]
	v_mfma_f32_16x16x32_bf16 v[96:99], v[164:167], v[236:239], v[96:99]
	v_mfma_f32_16x16x32_bf16 v[124:127], v[132:135], v[216:219], v[124:127]
	v_mfma_f32_16x16x32_bf16 v[120:123], v[168:171], v[216:219], v[120:123]
	v_mfma_f32_16x16x32_bf16 v[116:119], v[132:135], v[224:227], v[116:119]
	v_mfma_f32_16x16x32_bf16 v[112:115], v[168:171], v[224:227], v[112:115]
	v_mfma_f32_16x16x32_bf16 v[108:111], v[132:135], v[232:235], v[108:111]
	v_mfma_f32_16x16x32_bf16 v[104:107], v[168:171], v[232:235], v[104:107]
	v_mfma_f32_16x16x32_bf16 v[100:103], v[132:135], v[240:243], v[100:103]
	v_mfma_f32_16x16x32_bf16 v[96:99], v[168:171], v[240:243], v[96:99]
	v_mfma_f32_16x16x32_bf16 v[60:63], v[172:175], v[212:215], v[60:63]
	v_mfma_f32_16x16x32_bf16 v[56:59], v[186:189], v[212:215], v[56:59]
	v_mfma_f32_16x16x32_bf16 v[52:55], v[172:175], v[220:223], v[52:55]
	v_mfma_f32_16x16x32_bf16 v[48:51], v[186:189], v[220:223], v[48:51]
	v_mfma_f32_16x16x32_bf16 v[44:47], v[172:175], v[228:231], v[44:47]
	v_mfma_f32_16x16x32_bf16 v[40:43], v[186:189], v[228:231], v[40:43]
	v_mfma_f32_16x16x32_bf16 v[36:39], v[172:175], v[236:239], v[36:39]
	v_mfma_f32_16x16x32_bf16 v[32:35], v[186:189], v[236:239], v[32:35]
	v_mfma_f32_16x16x32_bf16 v[60:63], v[182:185], v[216:219], v[60:63]
	v_mfma_f32_16x16x32_bf16 v[56:59], v[208:211], v[216:219], v[56:59]
	v_mfma_f32_16x16x32_bf16 v[52:55], v[182:185], v[224:227], v[52:55]
	v_mfma_f32_16x16x32_bf16 v[48:51], v[208:211], v[224:227], v[48:51]
	v_mfma_f32_16x16x32_bf16 v[44:47], v[182:185], v[232:235], v[44:47]
	v_mfma_f32_16x16x32_bf16 v[40:43], v[208:211], v[232:235], v[40:43]
	v_mfma_f32_16x16x32_bf16 v[36:39], v[182:185], v[240:243], v[36:39]
	v_mfma_f32_16x16x32_bf16 v[32:35], v[208:211], v[240:243], v[32:35]
	s_barrier
	s_add_i32 s0, s0, s35
	v_lshl_add_u64 v[178:179], v[178:179], 0, s[26:27]
	s_mov_b32 m0, s0
	ds_read_b128 v[212:215], v181 offset:49152
	ds_read_b128 v[216:219], v181 offset:50176
	ds_read_b128 v[220:223], v181 offset:51200
	ds_read_b128 v[224:227], v181 offset:52224
	ds_read_b128 v[228:231], v181 offset:53248
	ds_read_b128 v[232:235], v181 offset:54272
	ds_read_b128 v[236:239], v181 offset:55296
	ds_read_b128 v[240:243], v181 offset:56320
	global_load_lds_dwordx4 v[178:179], off
	s_add_i32 m0, s0, 0x2000
	s_add_u32 s52, s58, 0x10080
	v_lshl_add_u64 v[178:179], v[244:245], 0, s[26:27]
	s_addc_u32 s53, s59, 0
	s_add_i32 s0, s37, s35
	global_load_lds_dwordx4 v[178:179], off
	v_lshl_add_u64 v[178:179], s[52:53], 0, v[140:141]
	s_mov_b32 m0, s0
	s_nop 0
	global_load_lds_dwordx4 v[178:179], off
	v_lshl_add_u64 v[178:179], s[52:53], 0, v[136:137]
	s_add_i32 m0, s0, 0x2000
	s_nop 0
	global_load_lds_dwordx4 v[178:179], off
	v_lshl_add_u64 v[178:179], v[246:247], 0, s[26:27]
	s_mov_b32 m0, s48
	s_nop 0
	global_load_lds_dwordx4 v[178:179], off
	v_lshl_add_u64 v[178:179], v[248:249], 0, s[26:27]
	s_mov_b32 m0, s49
	s_nop 0
	global_load_lds_dwordx4 v[178:179], off
	s_waitcnt vmcnt(8)
	s_waitcnt lgkmcnt(0)
	s_barrier
	s_waitcnt lgkmcnt(0)
	v_mfma_f32_16x16x32_bf16 v[92:95], v[128:131], v[212:215], v[92:95]
	v_mfma_f32_16x16x32_bf16 v[88:91], v[164:167], v[212:215], v[88:91]
	v_mfma_f32_16x16x32_bf16 v[84:87], v[128:131], v[220:223], v[84:87]
	v_mfma_f32_16x16x32_bf16 v[80:83], v[164:167], v[220:223], v[80:83]
	v_mfma_f32_16x16x32_bf16 v[76:79], v[128:131], v[228:231], v[76:79]
	v_mfma_f32_16x16x32_bf16 v[72:75], v[164:167], v[228:231], v[72:75]
	v_mfma_f32_16x16x32_bf16 v[68:71], v[128:131], v[236:239], v[68:71]
	v_mfma_f32_16x16x32_bf16 v[64:67], v[164:167], v[236:239], v[64:67]
	v_mfma_f32_16x16x32_bf16 v[92:95], v[132:135], v[216:219], v[92:95]
	v_mfma_f32_16x16x32_bf16 v[88:91], v[168:171], v[216:219], v[88:91]
	v_mfma_f32_16x16x32_bf16 v[84:87], v[132:135], v[224:227], v[84:87]
	v_mfma_f32_16x16x32_bf16 v[80:83], v[168:171], v[224:227], v[80:83]
	v_mfma_f32_16x16x32_bf16 v[76:79], v[132:135], v[232:235], v[76:79]
	v_mfma_f32_16x16x32_bf16 v[72:75], v[168:171], v[232:235], v[72:75]
	v_mfma_f32_16x16x32_bf16 v[68:71], v[132:135], v[240:243], v[68:71]
	v_mfma_f32_16x16x32_bf16 v[64:67], v[168:171], v[240:243], v[64:67]
	v_mfma_f32_16x16x32_bf16 v[28:31], v[172:175], v[212:215], v[28:31]
	v_mfma_f32_16x16x32_bf16 v[24:27], v[186:189], v[212:215], v[24:27]
	v_mfma_f32_16x16x32_bf16 v[20:23], v[172:175], v[220:223], v[20:23]
	v_mfma_f32_16x16x32_bf16 v[16:19], v[186:189], v[220:223], v[16:19]
	v_mfma_f32_16x16x32_bf16 v[12:15], v[172:175], v[228:231], v[12:15]
	v_mfma_f32_16x16x32_bf16 v[8:11], v[186:189], v[228:231], v[8:11]
	v_mfma_f32_16x16x32_bf16 v[4:7], v[172:175], v[236:239], v[4:7]
	v_mfma_f32_16x16x32_bf16 v[0:3], v[186:189], v[236:239], v[0:3]
	v_mfma_f32_16x16x32_bf16 v[28:31], v[182:185], v[216:219], v[28:31]
	v_mfma_f32_16x16x32_bf16 v[24:27], v[208:211], v[216:219], v[24:27]
	v_mfma_f32_16x16x32_bf16 v[20:23], v[182:185], v[224:227], v[20:23]
	v_mfma_f32_16x16x32_bf16 v[16:19], v[208:211], v[224:227], v[16:19]
	v_mfma_f32_16x16x32_bf16 v[12:15], v[182:185], v[232:235], v[12:15]
	v_mfma_f32_16x16x32_bf16 v[8:11], v[208:211], v[232:235], v[8:11]
	v_mfma_f32_16x16x32_bf16 v[4:7], v[182:185], v[240:243], v[4:7]
	v_mfma_f32_16x16x32_bf16 v[0:3], v[208:211], v[240:243], v[0:3]
	s_barrier
	s_add_i32 s70, s70, 2
	s_add_u32 s56, s56, 0x100
	s_addc_u32 s57, s57, 0
	s_add_u32 s64, s64, 0x100
	s_addc_u32 s65, s65, 0
	s_cmp_gt_u32 s70, 13
	s_cbranch_scc0 .LBB0_116
	v_readlane_b32 s4, v252, 28
	v_readlane_b32 s5, v252, 29
	s_and_b64 vcc, exec, s[4:5]
	s_cbranch_vccz .LBB0_119
	s_barrier

.LBB0_154:
	s_add_u32 s37, s54, 0xfff80080
	s_addc_u32 s39, s55, -1
	s_add_i32 s45, 0, 0x10000
	s_cmp_eq_u32 s30, 4
	s_cselect_b32 s61, s51, s39
	s_cselect_b32 s60, s50, s37
	v_add_u32_e32 v120, s45, v207
	s_cselect_b32 s57, s53, s21
	s_cselect_b32 s56, s52, s20
	s_add_i32 s37, 0, 0x14000
	ds_read_b128 v[130:133], v120
	ds_read_b128 v[134:137], v120 offset:1024
	ds_read_b128 v[138:141], v120 offset:2048
	ds_read_b128 v[142:145], v120 offset:3072
	v_add_u32_e32 v120, s37, v207
	ds_read_b128 v[146:149], v120
	ds_read_b128 v[150:153], v120 offset:1024
	ds_read_b128 v[154:157], v120 offset:2048
	ds_read_b128 v[158:161], v120 offset:3072
	v_lshl_add_u64 v[120:121], s[54:55], 0, v[178:179]
	s_add_i32 m0, s35, 0xc000
	ds_read_b128 v[182:185], v209
	ds_read_b128 v[186:189], v209 offset:1024
	ds_read_b128 v[210:213], v209 offset:2048
	ds_read_b128 v[214:217], v209 offset:3072
	ds_read_b128 v[218:221], v209 offset:4096
	ds_read_b128 v[222:225], v209 offset:5120
	ds_read_b128 v[226:229], v209 offset:6144
	ds_read_b128 v[230:233], v209 offset:7168
	global_load_lds_dwordx4 v[120:121], off
	v_lshl_add_u64 v[120:121], s[54:55], 0, v[180:181]
	s_add_i32 m0, s35, 0xe000
	s_nop 0
	global_load_lds_dwordx4 v[120:121], off
	s_waitcnt vmcnt(8)
	s_waitcnt lgkmcnt(0)
	s_barrier
	s_waitcnt lgkmcnt(0)
	v_mfma_f32_16x16x32_bf16 v[126:129], v[130:133], v[182:185], v[126:129]
	v_mfma_f32_16x16x32_bf16 v[120:123], v[138:141], v[182:185], v[122:125]
	v_mfma_f32_16x16x32_bf16 v[108:111], v[130:133], v[210:213], v[108:111]
	v_mfma_f32_16x16x32_bf16 v[104:107], v[138:141], v[210:213], v[104:107]
	v_mfma_f32_16x16x32_bf16 v[92:95], v[130:133], v[218:221], v[92:95]
	v_mfma_f32_16x16x32_bf16 v[88:91], v[138:141], v[218:221], v[88:91]
	v_mfma_f32_16x16x32_bf16 v[76:79], v[130:133], v[226:229], v[76:79]
	v_mfma_f32_16x16x32_bf16 v[72:75], v[138:141], v[226:229], v[72:75]
	v_mfma_f32_16x16x32_bf16 v[126:129], v[134:137], v[186:189], v[126:129]
	v_mfma_f32_16x16x32_bf16 v[120:123], v[142:145], v[186:189], v[120:123]
	v_mfma_f32_16x16x32_bf16 v[108:111], v[134:137], v[214:217], v[108:111]
	v_mfma_f32_16x16x32_bf16 v[104:107], v[142:145], v[214:217], v[104:107]
	v_mfma_f32_16x16x32_bf16 v[92:95], v[134:137], v[222:225], v[92:95]
	v_mfma_f32_16x16x32_bf16 v[88:91], v[142:145], v[222:225], v[88:91]
	v_mfma_f32_16x16x32_bf16 v[76:79], v[134:137], v[230:233], v[76:79]
	v_mfma_f32_16x16x32_bf16 v[72:75], v[142:145], v[230:233], v[72:75]
	v_mfma_f32_16x16x32_bf16 v[116:119], v[146:149], v[182:185], v[116:119]
	v_mfma_f32_16x16x32_bf16 v[112:115], v[154:157], v[182:185], v[112:115]
	v_mfma_f32_16x16x32_bf16 v[100:103], v[146:149], v[210:213], v[100:103]
	v_mfma_f32_16x16x32_bf16 v[96:99], v[154:157], v[210:213], v[96:99]
	v_mfma_f32_16x16x32_bf16 v[84:87], v[146:149], v[218:221], v[84:87]
	v_mfma_f32_16x16x32_bf16 v[80:83], v[154:157], v[218:221], v[80:83]
	v_mfma_f32_16x16x32_bf16 v[68:71], v[146:149], v[226:229], v[68:71]
	v_mfma_f32_16x16x32_bf16 v[64:67], v[154:157], v[226:229], v[64:67]
	v_mfma_f32_16x16x32_bf16 v[116:119], v[150:153], v[186:189], v[116:119]
	v_mfma_f32_16x16x32_bf16 v[112:115], v[158:161], v[186:189], v[112:115]
	v_mfma_f32_16x16x32_bf16 v[100:103], v[150:153], v[214:217], v[100:103]
	v_mfma_f32_16x16x32_bf16 v[96:99], v[158:161], v[214:217], v[96:99]
	v_mfma_f32_16x16x32_bf16 v[84:87], v[150:153], v[222:225], v[84:87]
	v_mfma_f32_16x16x32_bf16 v[80:83], v[158:161], v[222:225], v[80:83]
	v_mfma_f32_16x16x32_bf16 v[68:71], v[150:153], v[230:233], v[68:71]
	v_mfma_f32_16x16x32_bf16 v[64:67], v[158:161], v[230:233], v[64:67]
	s_barrier
	s_add_i32 s39, s45, s34
	v_lshl_add_u64 v[234:235], s[56:57], 0, v[176:177]
	s_mov_b32 m0, s39
	ds_read_b128 v[182:185], v209 offset:16384
	ds_read_b128 v[186:189], v209 offset:17408
	ds_read_b128 v[210:213], v209 offset:18432
	ds_read_b128 v[214:217], v209 offset:19456
	ds_read_b128 v[218:221], v209 offset:20480
	ds_read_b128 v[222:225], v209 offset:21504
	ds_read_b128 v[226:229], v209 offset:22528
	ds_read_b128 v[230:233], v209 offset:23552
	global_load_lds_dwordx4 v[234:235], off
	s_add_i32 m0, s39, 0x2000
	s_add_u32 s88, s56, 0x20000
	v_lshl_add_u64 v[236:237], s[56:57], 0, v[166:167]
	s_addc_u32 s89, s57, 0
	s_add_i32 s37, s37, s34
	global_load_lds_dwordx4 v[236:237], off
	v_lshl_add_u64 v[124:125], s[88:89], 0, v[176:177]
	s_mov_b32 m0, s37
	v_lshl_add_u64 v[238:239], s[60:61], 0, v[162:163]
	global_load_lds_dwordx4 v[124:125], off
	v_lshl_add_u64 v[124:125], s[88:89], 0, v[166:167]
	s_add_i32 m0, s37, 0x2000
	v_lshl_add_u64 v[240:241], s[60:61], 0, v[164:165]
	global_load_lds_dwordx4 v[124:125], off
	s_mov_b32 m0, s35
	s_nop 0
	global_load_lds_dwordx4 v[238:239], off
	s_mov_b32 m0, s62
	s_nop 0
	global_load_lds_dwordx4 v[240:241], off
	s_waitcnt vmcnt(8)
	s_waitcnt lgkmcnt(0)
	s_barrier
	s_waitcnt lgkmcnt(0)
	v_mfma_f32_16x16x32_bf16 v[60:63], v[130:133], v[182:185], v[60:63]
	v_mfma_f32_16x16x32_bf16 v[56:59], v[138:141], v[182:185], v[56:59]
	v_mfma_f32_16x16x32_bf16 v[44:47], v[130:133], v[210:213], v[44:47]
	v_mfma_f32_16x16x32_bf16 v[40:43], v[138:141], v[210:213], v[40:43]
	v_mfma_f32_16x16x32_bf16 v[28:31], v[130:133], v[218:221], v[28:31]
	v_mfma_f32_16x16x32_bf16 v[24:27], v[138:141], v[218:221], v[24:27]
	v_mfma_f32_16x16x32_bf16 v[12:15], v[130:133], v[226:229], v[12:15]
	v_mfma_f32_16x16x32_bf16 v[8:11], v[138:141], v[226:229], v[8:11]
	v_mfma_f32_16x16x32_bf16 v[60:63], v[134:137], v[186:189], v[60:63]
	v_mfma_f32_16x16x32_bf16 v[56:59], v[142:145], v[186:189], v[56:59]
	v_mfma_f32_16x16x32_bf16 v[44:47], v[134:137], v[214:217], v[44:47]
	v_mfma_f32_16x16x32_bf16 v[40:43], v[142:145], v[214:217], v[40:43]
	v_mfma_f32_16x16x32_bf16 v[28:31], v[134:137], v[222:225], v[28:31]
	v_mfma_f32_16x16x32_bf16 v[24:27], v[142:145], v[222:225], v[24:27]
	v_mfma_f32_16x16x32_bf16 v[12:15], v[134:137], v[230:233], v[12:15]
	v_mfma_f32_16x16x32_bf16 v[8:11], v[142:145], v[230:233], v[8:11]
	v_mfma_f32_16x16x32_bf16 v[52:55], v[146:149], v[182:185], v[52:55]
	v_mfma_f32_16x16x32_bf16 v[48:51], v[154:157], v[182:185], v[48:51]
	v_mfma_f32_16x16x32_bf16 v[36:39], v[146:149], v[210:213], v[36:39]
	v_mfma_f32_16x16x32_bf16 v[32:35], v[154:157], v[210:213], v[32:35]
	v_mfma_f32_16x16x32_bf16 v[20:23], v[146:149], v[218:221], v[20:23]
	v_mfma_f32_16x16x32_bf16 v[16:19], v[154:157], v[218:221], v[16:19]
	v_mfma_f32_16x16x32_bf16 v[4:7], v[146:149], v[226:229], v[4:7]
	v_mfma_f32_16x16x32_bf16 v[0:3], v[154:157], v[226:229], v[0:3]
	v_mfma_f32_16x16x32_bf16 v[52:55], v[150:153], v[186:189], v[52:55]
	v_mfma_f32_16x16x32_bf16 v[48:51], v[158:161], v[186:189], v[48:51]
	v_mfma_f32_16x16x32_bf16 v[36:39], v[150:153], v[214:217], v[36:39]
	v_mfma_f32_16x16x32_bf16 v[32:35], v[158:161], v[214:217], v[32:35]
	v_mfma_f32_16x16x32_bf16 v[20:23], v[150:153], v[222:225], v[20:23]
	v_mfma_f32_16x16x32_bf16 v[16:19], v[158:161], v[222:225], v[16:19]
	v_mfma_f32_16x16x32_bf16 v[4:7], v[150:153], v[230:233], v[4:7]
	v_mfma_f32_16x16x32_bf16 v[0:3], v[158:161], v[230:233], v[0:3]
	s_barrier
	s_add_i32 s37, 0, 0x18000
	v_add_u32_e32 v124, s37, v207
	s_add_i32 s39, 0, 0x1c000
	ds_read_b128 v[130:133], v124
	ds_read_b128 v[134:137], v124 offset:1024
	ds_read_b128 v[138:141], v124 offset:2048
	ds_read_b128 v[142:145], v124 offset:3072
	v_add_u32_e32 v124, s39, v207
	ds_read_b128 v[146:149], v124
	ds_read_b128 v[150:153], v124 offset:1024
	ds_read_b128 v[154:157], v124 offset:2048
	ds_read_b128 v[158:161], v124 offset:3072
	s_add_u32 s60, s60, 0x80000
	s_addc_u32 s61, s61, 0
	s_mov_b32 m0, s63
	v_lshl_add_u64 v[124:125], s[60:61], 0, v[162:163]
	ds_read_b128 v[182:185], v209 offset:32768
	ds_read_b128 v[186:189], v209 offset:33792
	ds_read_b128 v[210:213], v209 offset:34816
	ds_read_b128 v[214:217], v209 offset:35840
	ds_read_b128 v[218:221], v209 offset:36864
	ds_read_b128 v[222:225], v209 offset:37888
	ds_read_b128 v[226:229], v209 offset:38912
	ds_read_b128 v[230:233], v209 offset:39936
	global_load_lds_dwordx4 v[124:125], off
	v_lshl_add_u64 v[124:125], s[60:61], 0, v[164:165]
	s_mov_b32 m0, s64
	s_nop 0
	global_load_lds_dwordx4 v[124:125], off
	s_waitcnt vmcnt(8)
	s_waitcnt lgkmcnt(0)
	s_barrier
	s_waitcnt lgkmcnt(0)
	v_mfma_f32_16x16x32_bf16 v[124:127], v[130:133], v[182:185], v[126:129]
	v_mfma_f32_16x16x32_bf16 v[120:123], v[138:141], v[182:185], v[120:123]
	v_mfma_f32_16x16x32_bf16 v[108:111], v[130:133], v[210:213], v[108:111]
	v_mfma_f32_16x16x32_bf16 v[104:107], v[138:141], v[210:213], v[104:107]
	v_mfma_f32_16x16x32_bf16 v[92:95], v[130:133], v[218:221], v[92:95]
	v_mfma_f32_16x16x32_bf16 v[88:91], v[138:141], v[218:221], v[88:91]
	v_mfma_f32_16x16x32_bf16 v[76:79], v[130:133], v[226:229], v[76:79]
	v_mfma_f32_16x16x32_bf16 v[72:75], v[138:141], v[226:229], v[72:75]
	v_mfma_f32_16x16x32_bf16 v[126:129], v[134:137], v[186:189], v[124:127]
	v_mfma_f32_16x16x32_bf16 v[122:125], v[142:145], v[186:189], v[120:123]
	v_mfma_f32_16x16x32_bf16 v[108:111], v[134:137], v[214:217], v[108:111]
	v_mfma_f32_16x16x32_bf16 v[104:107], v[142:145], v[214:217], v[104:107]
	v_mfma_f32_16x16x32_bf16 v[92:95], v[134:137], v[222:225], v[92:95]
	v_mfma_f32_16x16x32_bf16 v[88:91], v[142:145], v[222:225], v[88:91]
	v_mfma_f32_16x16x32_bf16 v[76:79], v[134:137], v[230:233], v[76:79]
	v_mfma_f32_16x16x32_bf16 v[72:75], v[142:145], v[230:233], v[72:75]
	v_mfma_f32_16x16x32_bf16 v[116:119], v[146:149], v[182:185], v[116:119]
	v_mfma_f32_16x16x32_bf16 v[112:115], v[154:157], v[182:185], v[112:115]
	v_mfma_f32_16x16x32_bf16 v[100:103], v[146:149], v[210:213], v[100:103]
	v_mfma_f32_16x16x32_bf16 v[96:99], v[154:157], v[210:213], v[96:99]
	v_mfma_f32_16x16x32_bf16 v[84:87], v[146:149], v[218:221], v[84:87]
	v_mfma_f32_16x16x32_bf16 v[80:83], v[154:157], v[218:221], v[80:83]
	v_mfma_f32_16x16x32_bf16 v[68:71], v[146:149], v[226:229], v[68:71]
	v_mfma_f32_16x16x32_bf16 v[64:67], v[154:157], v[226:229], v[64:67]
	v_mfma_f32_16x16x32_bf16 v[116:119], v[150:153], v[186:189], v[116:119]
	v_mfma_f32_16x16x32_bf16 v[112:115], v[158:161], v[186:189], v[112:115]
	v_mfma_f32_16x16x32_bf16 v[100:103], v[150:153], v[214:217], v[100:103]
	v_mfma_f32_16x16x32_bf16 v[96:99], v[158:161], v[214:217], v[96:99]
	v_mfma_f32_16x16x32_bf16 v[84:87], v[150:153], v[222:225], v[84:87]
	v_mfma_f32_16x16x32_bf16 v[80:83], v[158:161], v[222:225], v[80:83]
	v_mfma_f32_16x16x32_bf16 v[68:71], v[150:153], v[230:233], v[68:71]
	v_mfma_f32_16x16x32_bf16 v[64:67], v[158:161], v[230:233], v[64:67]
	s_barrier
	s_add_i32 s37, s37, s34
	v_lshl_add_u64 v[120:121], v[234:235], 0, s[26:27]
	s_mov_b32 m0, s37
	ds_read_b128 v[182:185], v209 offset:49152
	ds_read_b128 v[186:189], v209 offset:50176
	ds_read_b128 v[210:213], v209 offset:51200
	ds_read_b128 v[214:217], v209 offset:52224
	ds_read_b128 v[218:221], v209 offset:53248
	ds_read_b128 v[222:225], v209 offset:54272
	ds_read_b128 v[226:229], v209 offset:55296
	ds_read_b128 v[230:233], v209 offset:56320
	global_load_lds_dwordx4 v[120:121], off
	s_add_i32 m0, s37, 0x2000
	s_add_u32 s56, s56, 0x20080
	v_lshl_add_u64 v[120:121], v[236:237], 0, s[26:27]
	s_addc_u32 s57, s57, 0
	s_add_i32 s37, s39, s34
	global_load_lds_dwordx4 v[120:121], off
	v_lshl_add_u64 v[120:121], s[56:57], 0, v[176:177]
	s_mov_b32 m0, s37
	s_nop 0
	global_load_lds_dwordx4 v[120:121], off
	v_lshl_add_u64 v[120:121], s[56:57], 0, v[166:167]
	s_add_i32 m0, s37, 0x2000
	s_nop 0
	global_load_lds_dwordx4 v[120:121], off
	v_lshl_add_u64 v[120:121], v[238:239], 0, s[26:27]
	s_mov_b32 m0, s65
	s_nop 0
	global_load_lds_dwordx4 v[120:121], off
	v_lshl_add_u64 v[120:121], v[240:241], 0, s[26:27]
	s_mov_b32 m0, s66
	s_nop 0
	global_load_lds_dwordx4 v[120:121], off
	s_waitcnt vmcnt(8)
	s_waitcnt lgkmcnt(0)
	s_barrier
	s_waitcnt lgkmcnt(0)
	v_mfma_f32_16x16x32_bf16 v[60:63], v[130:133], v[182:185], v[60:63]
	v_mfma_f32_16x16x32_bf16 v[56:59], v[138:141], v[182:185], v[56:59]
	v_mfma_f32_16x16x32_bf16 v[44:47], v[130:133], v[210:213], v[44:47]
	v_mfma_f32_16x16x32_bf16 v[40:43], v[138:141], v[210:213], v[40:43]
	v_mfma_f32_16x16x32_bf16 v[28:31], v[130:133], v[218:221], v[28:31]
	v_mfma_f32_16x16x32_bf16 v[24:27], v[138:141], v[218:221], v[24:27]
	v_mfma_f32_16x16x32_bf16 v[12:15], v[130:133], v[226:229], v[12:15]
	v_mfma_f32_16x16x32_bf16 v[8:11], v[138:141], v[226:229], v[8:11]
	v_mfma_f32_16x16x32_bf16 v[60:63], v[134:137], v[186:189], v[60:63]
	v_mfma_f32_16x16x32_bf16 v[56:59], v[142:145], v[186:189], v[56:59]
	v_mfma_f32_16x16x32_bf16 v[44:47], v[134:137], v[214:217], v[44:47]
	v_mfma_f32_16x16x32_bf16 v[40:43], v[142:145], v[214:217], v[40:43]
	v_mfma_f32_16x16x32_bf16 v[28:31], v[134:137], v[222:225], v[28:31]
	v_mfma_f32_16x16x32_bf16 v[24:27], v[142:145], v[222:225], v[24:27]
	v_mfma_f32_16x16x32_bf16 v[12:15], v[134:137], v[230:233], v[12:15]
	v_mfma_f32_16x16x32_bf16 v[8:11], v[142:145], v[230:233], v[8:11]
	v_mfma_f32_16x16x32_bf16 v[52:55], v[146:149], v[182:185], v[52:55]
	v_mfma_f32_16x16x32_bf16 v[48:51], v[154:157], v[182:185], v[48:51]
	v_mfma_f32_16x16x32_bf16 v[36:39], v[146:149], v[210:213], v[36:39]
	v_mfma_f32_16x16x32_bf16 v[32:35], v[154:157], v[210:213], v[32:35]
	v_mfma_f32_16x16x32_bf16 v[20:23], v[146:149], v[218:221], v[20:23]
	v_mfma_f32_16x16x32_bf16 v[16:19], v[154:157], v[218:221], v[16:19]
	v_mfma_f32_16x16x32_bf16 v[4:7], v[146:149], v[226:229], v[4:7]
	v_mfma_f32_16x16x32_bf16 v[0:3], v[154:157], v[226:229], v[0:3]
	v_mfma_f32_16x16x32_bf16 v[52:55], v[150:153], v[186:189], v[52:55]
	v_mfma_f32_16x16x32_bf16 v[48:51], v[158:161], v[186:189], v[48:51]
	v_mfma_f32_16x16x32_bf16 v[36:39], v[150:153], v[214:217], v[36:39]
	v_mfma_f32_16x16x32_bf16 v[32:35], v[158:161], v[214:217], v[32:35]
	v_mfma_f32_16x16x32_bf16 v[20:23], v[150:153], v[222:225], v[20:23]
	v_mfma_f32_16x16x32_bf16 v[16:19], v[158:161], v[222:225], v[16:19]
	v_mfma_f32_16x16x32_bf16 v[4:7], v[150:153], v[230:233], v[4:7]
	v_mfma_f32_16x16x32_bf16 v[0:3], v[158:161], v[230:233], v[0:3]
	s_barrier
	s_add_i32 s30, s30, 2
	s_add_u32 s54, s54, 0x100
	s_addc_u32 s55, s55, 0
	s_add_u32 s20, s20, 0x100
	s_addc_u32 s21, s21, 0
	s_cmp_gt_u32 s30, 5
	s_cbranch_scc0 .LBB0_154
	s_and_b64 vcc, exec, s[48:49]
	s_cbranch_vccz .LBB0_157
	s_barrier

.LBB0_645:
	s_add_u32 s37, s42, 0xfffc0080
	s_addc_u32 s39, s43, -1
	s_add_i32 s65, 0, 0x10000
	s_cmp_eq_u32 s64, 12
	s_cselect_b32 s63, s0, s39
	s_cselect_b32 s62, s1, s37
	v_add_u32_e32 v145, s65, v162
	s_cselect_b32 s45, s20, s30
	s_cselect_b32 s44, s21, s22
	s_add_i32 s37, 0, 0x14000
	ds_read_b128 v[146:149], v145
	ds_read_b128 v[150:153], v145 offset:1024
	ds_read_b128 v[154:157], v145 offset:2048
	ds_read_b128 v[170:173], v145 offset:3072
	v_add_u32_e32 v145, s37, v162
	ds_read_b128 v[178:181], v145
	ds_read_b128 v[182:185], v145 offset:1024
	ds_read_b128 v[186:189], v145 offset:2048
	ds_read_b128 v[208:211], v145 offset:3072
	v_lshl_add_u64 v[158:159], s[42:43], 0, v[140:141]
	s_add_i32 m0, s56, 0xc000
	ds_read_b128 v[212:215], v168
	ds_read_b128 v[216:219], v168 offset:1024
	ds_read_b128 v[220:223], v168 offset:2048
	ds_read_b128 v[224:227], v168 offset:3072
	ds_read_b128 v[228:231], v168 offset:4096
	ds_read_b128 v[232:235], v168 offset:5120
	ds_read_b128 v[236:239], v168 offset:6144
	ds_read_b128 v[240:243], v168 offset:7168
	global_load_lds_dwordx4 v[158:159], off
	v_lshl_add_u64 v[158:159], s[42:43], 0, v[142:143]
	s_add_i32 m0, s56, 0xe000
	s_nop 0
	global_load_lds_dwordx4 v[158:159], off
	s_waitcnt vmcnt(8)
	s_waitcnt lgkmcnt(0)
	s_barrier
	s_waitcnt lgkmcnt(0)
	v_mfma_f32_16x16x32_bf16 v[124:127], v[146:149], v[212:215], v[124:127]
	v_mfma_f32_16x16x32_bf16 v[120:123], v[154:157], v[212:215], v[120:123]
	v_mfma_f32_16x16x32_bf16 v[116:119], v[146:149], v[220:223], v[116:119]
	v_mfma_f32_16x16x32_bf16 v[112:115], v[154:157], v[220:223], v[112:115]
	v_mfma_f32_16x16x32_bf16 v[100:103], v[146:149], v[228:231], v[100:103]
	v_mfma_f32_16x16x32_bf16 v[96:99], v[154:157], v[228:231], v[96:99]
	v_mfma_f32_16x16x32_bf16 v[84:87], v[146:149], v[236:239], v[84:87]
	v_mfma_f32_16x16x32_bf16 v[80:83], v[154:157], v[236:239], v[80:83]
	v_mfma_f32_16x16x32_bf16 v[124:127], v[150:153], v[216:219], v[124:127]
	v_mfma_f32_16x16x32_bf16 v[120:123], v[170:173], v[216:219], v[120:123]
	v_mfma_f32_16x16x32_bf16 v[116:119], v[150:153], v[224:227], v[116:119]
	v_mfma_f32_16x16x32_bf16 v[112:115], v[170:173], v[224:227], v[112:115]
	v_mfma_f32_16x16x32_bf16 v[100:103], v[150:153], v[232:235], v[100:103]
	v_mfma_f32_16x16x32_bf16 v[96:99], v[170:173], v[232:235], v[96:99]
	v_mfma_f32_16x16x32_bf16 v[84:87], v[150:153], v[240:243], v[84:87]
	v_mfma_f32_16x16x32_bf16 v[80:83], v[170:173], v[240:243], v[80:83]
	v_mfma_f32_16x16x32_bf16 v[108:111], v[178:181], v[212:215], v[108:111]
	v_mfma_f32_16x16x32_bf16 v[104:107], v[186:189], v[212:215], v[104:107]
	v_mfma_f32_16x16x32_bf16 v[92:95], v[178:181], v[220:223], v[92:95]
	v_mfma_f32_16x16x32_bf16 v[88:91], v[186:189], v[220:223], v[88:91]
	v_mfma_f32_16x16x32_bf16 v[76:79], v[178:181], v[228:231], v[76:79]
	v_mfma_f32_16x16x32_bf16 v[72:75], v[186:189], v[228:231], v[72:75]
	v_mfma_f32_16x16x32_bf16 v[68:71], v[178:181], v[236:239], v[68:71]
	v_mfma_f32_16x16x32_bf16 v[64:67], v[186:189], v[236:239], v[64:67]
	v_mfma_f32_16x16x32_bf16 v[108:111], v[182:185], v[216:219], v[108:111]
	v_mfma_f32_16x16x32_bf16 v[104:107], v[208:211], v[216:219], v[104:107]
	v_mfma_f32_16x16x32_bf16 v[92:95], v[182:185], v[224:227], v[92:95]
	v_mfma_f32_16x16x32_bf16 v[88:91], v[208:211], v[224:227], v[88:91]
	v_mfma_f32_16x16x32_bf16 v[76:79], v[182:185], v[232:235], v[76:79]
	v_mfma_f32_16x16x32_bf16 v[72:75], v[208:211], v[232:235], v[72:75]
	v_mfma_f32_16x16x32_bf16 v[68:71], v[182:185], v[240:243], v[68:71]
	v_mfma_f32_16x16x32_bf16 v[64:67], v[208:211], v[240:243], v[64:67]
	s_barrier
	s_add_i32 s39, s65, s52
	v_lshl_add_u64 v[158:159], s[44:45], 0, v[132:133]
	s_mov_b32 m0, s39
	ds_read_b128 v[212:215], v168 offset:16384
	ds_read_b128 v[216:219], v168 offset:17408
	ds_read_b128 v[220:223], v168 offset:18432
	ds_read_b128 v[224:227], v168 offset:19456
	ds_read_b128 v[228:231], v168 offset:20480
	ds_read_b128 v[232:235], v168 offset:21504
	ds_read_b128 v[236:239], v168 offset:22528
	ds_read_b128 v[240:243], v168 offset:23552
	global_load_lds_dwordx4 v[158:159], off
	s_add_i32 m0, s39, 0x2000
	s_add_u32 s66, s44, 0x10000
	v_lshl_add_u64 v[174:175], s[44:45], 0, v[128:129]
	s_addc_u32 s67, s45, 0
	s_add_i32 s37, s37, s52
	global_load_lds_dwordx4 v[174:175], off
	v_lshl_add_u64 v[244:245], s[66:67], 0, v[132:133]
	s_mov_b32 m0, s37
	v_lshl_add_u64 v[246:247], s[62:63], 0, v[130:131]
	global_load_lds_dwordx4 v[244:245], off
	v_lshl_add_u64 v[244:245], s[66:67], 0, v[128:129]
	s_add_i32 m0, s37, 0x2000
	s_nop 0
	global_load_lds_dwordx4 v[244:245], off
	v_lshl_add_u64 v[244:245], s[62:63], 0, v[134:135]
	s_mov_b32 m0, s56
	s_nop 0
	global_load_lds_dwordx4 v[244:245], off
	s_mov_b32 m0, s57
	s_nop 0
	global_load_lds_dwordx4 v[246:247], off
	s_waitcnt vmcnt(8)
	s_waitcnt lgkmcnt(0)
	s_barrier
	s_waitcnt lgkmcnt(0)
	v_mfma_f32_16x16x32_bf16 v[60:63], v[146:149], v[212:215], v[60:63]
	v_mfma_f32_16x16x32_bf16 v[56:59], v[154:157], v[212:215], v[56:59]
	v_mfma_f32_16x16x32_bf16 v[52:55], v[146:149], v[220:223], v[52:55]
	v_mfma_f32_16x16x32_bf16 v[48:51], v[154:157], v[220:223], v[48:51]
	v_mfma_f32_16x16x32_bf16 v[36:39], v[146:149], v[228:231], v[36:39]
	v_mfma_f32_16x16x32_bf16 v[32:35], v[154:157], v[228:231], v[32:35]
	v_mfma_f32_16x16x32_bf16 v[20:23], v[146:149], v[236:239], v[20:23]
	v_mfma_f32_16x16x32_bf16 v[16:19], v[154:157], v[236:239], v[16:19]
	v_mfma_f32_16x16x32_bf16 v[60:63], v[150:153], v[216:219], v[60:63]
	v_mfma_f32_16x16x32_bf16 v[56:59], v[170:173], v[216:219], v[56:59]
	v_mfma_f32_16x16x32_bf16 v[52:55], v[150:153], v[224:227], v[52:55]
	v_mfma_f32_16x16x32_bf16 v[48:51], v[170:173], v[224:227], v[48:51]
	v_mfma_f32_16x16x32_bf16 v[36:39], v[150:153], v[232:235], v[36:39]
	v_mfma_f32_16x16x32_bf16 v[32:35], v[170:173], v[232:235], v[32:35]
	v_mfma_f32_16x16x32_bf16 v[20:23], v[150:153], v[240:243], v[20:23]
	v_mfma_f32_16x16x32_bf16 v[16:19], v[170:173], v[240:243], v[16:19]
	v_mfma_f32_16x16x32_bf16 v[44:47], v[178:181], v[212:215], v[44:47]
	v_mfma_f32_16x16x32_bf16 v[40:43], v[186:189], v[212:215], v[40:43]
	v_mfma_f32_16x16x32_bf16 v[28:31], v[178:181], v[220:223], v[28:31]
	v_mfma_f32_16x16x32_bf16 v[24:27], v[186:189], v[220:223], v[24:27]
	v_mfma_f32_16x16x32_bf16 v[12:15], v[178:181], v[228:231], v[12:15]
	v_mfma_f32_16x16x32_bf16 v[8:11], v[186:189], v[228:231], v[8:11]
	v_mfma_f32_16x16x32_bf16 v[4:7], v[178:181], v[236:239], v[4:7]
	v_mfma_f32_16x16x32_bf16 v[0:3], v[186:189], v[236:239], v[0:3]
	v_mfma_f32_16x16x32_bf16 v[44:47], v[182:185], v[216:219], v[44:47]
	v_mfma_f32_16x16x32_bf16 v[40:43], v[208:211], v[216:219], v[40:43]
	v_mfma_f32_16x16x32_bf16 v[28:31], v[182:185], v[224:227], v[28:31]
	v_mfma_f32_16x16x32_bf16 v[24:27], v[208:211], v[224:227], v[24:27]
	v_mfma_f32_16x16x32_bf16 v[12:15], v[182:185], v[232:235], v[12:15]
	v_mfma_f32_16x16x32_bf16 v[8:11], v[208:211], v[232:235], v[8:11]
	v_mfma_f32_16x16x32_bf16 v[4:7], v[182:185], v[240:243], v[4:7]
	v_mfma_f32_16x16x32_bf16 v[0:3], v[208:211], v[240:243], v[0:3]
	s_barrier
	s_add_i32 s37, 0, 0x18000
	v_add_u32_e32 v145, s37, v162
	s_add_i32 s39, 0, 0x1c000
	ds_read_b128 v[146:149], v145
	ds_read_b128 v[150:153], v145 offset:1024
	ds_read_b128 v[154:157], v145 offset:2048
	ds_read_b128 v[170:173], v145 offset:3072
	v_add_u32_e32 v145, s39, v162
	ds_read_b128 v[178:181], v145
	ds_read_b128 v[182:185], v145 offset:1024
	ds_read_b128 v[186:189], v145 offset:2048
	ds_read_b128 v[208:211], v145 offset:3072
	s_add_u32 s62, s62, 0x40000
	s_addc_u32 s63, s63, 0
	s_mov_b32 m0, s54
	v_lshl_add_u64 v[248:249], s[62:63], 0, v[134:135]
	ds_read_b128 v[212:215], v168 offset:32768
	ds_read_b128 v[216:219], v168 offset:33792
	ds_read_b128 v[220:223], v168 offset:34816
	ds_read_b128 v[224:227], v168 offset:35840
	ds_read_b128 v[228:231], v168 offset:36864
	ds_read_b128 v[232:235], v168 offset:37888
	ds_read_b128 v[236:239], v168 offset:38912
	ds_read_b128 v[240:243], v168 offset:39936
	global_load_lds_dwordx4 v[248:249], off
	v_lshl_add_u64 v[248:249], s[62:63], 0, v[130:131]
	s_mov_b32 m0, s55
	s_nop 0
	global_load_lds_dwordx4 v[248:249], off
	s_waitcnt vmcnt(8)
	s_waitcnt lgkmcnt(0)
	s_barrier
	s_waitcnt lgkmcnt(0)
	v_mfma_f32_16x16x32_bf16 v[124:127], v[146:149], v[212:215], v[124:127]
	v_mfma_f32_16x16x32_bf16 v[120:123], v[154:157], v[212:215], v[120:123]
	v_mfma_f32_16x16x32_bf16 v[116:119], v[146:149], v[220:223], v[116:119]
	v_mfma_f32_16x16x32_bf16 v[112:115], v[154:157], v[220:223], v[112:115]
	v_mfma_f32_16x16x32_bf16 v[100:103], v[146:149], v[228:231], v[100:103]
	v_mfma_f32_16x16x32_bf16 v[96:99], v[154:157], v[228:231], v[96:99]
	v_mfma_f32_16x16x32_bf16 v[84:87], v[146:149], v[236:239], v[84:87]
	v_mfma_f32_16x16x32_bf16 v[80:83], v[154:157], v[236:239], v[80:83]
	v_mfma_f32_16x16x32_bf16 v[124:127], v[150:153], v[216:219], v[124:127]
	v_mfma_f32_16x16x32_bf16 v[120:123], v[170:173], v[216:219], v[120:123]
	v_mfma_f32_16x16x32_bf16 v[116:119], v[150:153], v[224:227], v[116:119]
	v_mfma_f32_16x16x32_bf16 v[112:115], v[170:173], v[224:227], v[112:115]
	v_mfma_f32_16x16x32_bf16 v[100:103], v[150:153], v[232:235], v[100:103]
	v_mfma_f32_16x16x32_bf16 v[96:99], v[170:173], v[232:235], v[96:99]
	v_mfma_f32_16x16x32_bf16 v[84:87], v[150:153], v[240:243], v[84:87]
	v_mfma_f32_16x16x32_bf16 v[80:83], v[170:173], v[240:243], v[80:83]
	v_mfma_f32_16x16x32_bf16 v[108:111], v[178:181], v[212:215], v[108:111]
	v_mfma_f32_16x16x32_bf16 v[104:107], v[186:189], v[212:215], v[104:107]
	v_mfma_f32_16x16x32_bf16 v[92:95], v[178:181], v[220:223], v[92:95]
	v_mfma_f32_16x16x32_bf16 v[88:91], v[186:189], v[220:223], v[88:91]
	v_mfma_f32_16x16x32_bf16 v[76:79], v[178:181], v[228:231], v[76:79]
	v_mfma_f32_16x16x32_bf16 v[72:75], v[186:189], v[228:231], v[72:75]
	v_mfma_f32_16x16x32_bf16 v[68:71], v[178:181], v[236:239], v[68:71]
	v_mfma_f32_16x16x32_bf16 v[64:67], v[186:189], v[236:239], v[64:67]
	v_mfma_f32_16x16x32_bf16 v[108:111], v[182:185], v[216:219], v[108:111]
	v_mfma_f32_16x16x32_bf16 v[104:107], v[208:211], v[216:219], v[104:107]
	v_mfma_f32_16x16x32_bf16 v[92:95], v[182:185], v[224:227], v[92:95]
	v_mfma_f32_16x16x32_bf16 v[88:91], v[208:211], v[224:227], v[88:91]
	v_mfma_f32_16x16x32_bf16 v[76:79], v[182:185], v[232:235], v[76:79]
	v_mfma_f32_16x16x32_bf16 v[72:75], v[208:211], v[232:235], v[72:75]
	v_mfma_f32_16x16x32_bf16 v[68:71], v[182:185], v[240:243], v[68:71]
	v_mfma_f32_16x16x32_bf16 v[64:67], v[208:211], v[240:243], v[64:67]
	s_barrier
	s_add_i32 s37, s37, s52
	v_lshl_add_u64 v[158:159], v[158:159], 0, s[26:27]
	s_mov_b32 m0, s37
	ds_read_b128 v[212:215], v168 offset:49152
	ds_read_b128 v[216:219], v168 offset:50176
	ds_read_b128 v[220:223], v168 offset:51200
	ds_read_b128 v[224:227], v168 offset:52224
	ds_read_b128 v[228:231], v168 offset:53248
	ds_read_b128 v[232:235], v168 offset:54272
	ds_read_b128 v[236:239], v168 offset:55296
	ds_read_b128 v[240:243], v168 offset:56320
	global_load_lds_dwordx4 v[158:159], off
	s_add_i32 m0, s37, 0x2000
	s_add_u32 s44, s44, 0x10080
	v_lshl_add_u64 v[158:159], v[174:175], 0, s[26:27]
	s_addc_u32 s45, s45, 0
	s_add_i32 s37, s39, s52
	global_load_lds_dwordx4 v[158:159], off
	v_lshl_add_u64 v[158:159], s[44:45], 0, v[132:133]
	s_mov_b32 m0, s37
	s_nop 0
	global_load_lds_dwordx4 v[158:159], off
	v_lshl_add_u64 v[158:159], s[44:45], 0, v[128:129]
	s_add_i32 m0, s37, 0x2000
	s_nop 0
	global_load_lds_dwordx4 v[158:159], off
	v_lshl_add_u64 v[158:159], v[244:245], 0, s[26:27]
	s_mov_b32 m0, s34
	s_nop 0
	global_load_lds_dwordx4 v[158:159], off
	v_lshl_add_u64 v[158:159], v[246:247], 0, s[26:27]
	s_mov_b32 m0, s53
	s_nop 0
	global_load_lds_dwordx4 v[158:159], off
	s_waitcnt vmcnt(8)
	s_waitcnt lgkmcnt(0)
	s_barrier
	s_waitcnt lgkmcnt(0)
	v_mfma_f32_16x16x32_bf16 v[60:63], v[146:149], v[212:215], v[60:63]
	v_mfma_f32_16x16x32_bf16 v[56:59], v[154:157], v[212:215], v[56:59]
	v_mfma_f32_16x16x32_bf16 v[52:55], v[146:149], v[220:223], v[52:55]
	v_mfma_f32_16x16x32_bf16 v[48:51], v[154:157], v[220:223], v[48:51]
	v_mfma_f32_16x16x32_bf16 v[36:39], v[146:149], v[228:231], v[36:39]
	v_mfma_f32_16x16x32_bf16 v[32:35], v[154:157], v[228:231], v[32:35]
	v_mfma_f32_16x16x32_bf16 v[20:23], v[146:149], v[236:239], v[20:23]
	v_mfma_f32_16x16x32_bf16 v[16:19], v[154:157], v[236:239], v[16:19]
	v_mfma_f32_16x16x32_bf16 v[60:63], v[150:153], v[216:219], v[60:63]
	v_mfma_f32_16x16x32_bf16 v[56:59], v[170:173], v[216:219], v[56:59]
	v_mfma_f32_16x16x32_bf16 v[52:55], v[150:153], v[224:227], v[52:55]
	v_mfma_f32_16x16x32_bf16 v[48:51], v[170:173], v[224:227], v[48:51]
	v_mfma_f32_16x16x32_bf16 v[36:39], v[150:153], v[232:235], v[36:39]
	v_mfma_f32_16x16x32_bf16 v[32:35], v[170:173], v[232:235], v[32:35]
	v_mfma_f32_16x16x32_bf16 v[20:23], v[150:153], v[240:243], v[20:23]
	v_mfma_f32_16x16x32_bf16 v[16:19], v[170:173], v[240:243], v[16:19]
	v_mfma_f32_16x16x32_bf16 v[44:47], v[178:181], v[212:215], v[44:47]
	v_mfma_f32_16x16x32_bf16 v[40:43], v[186:189], v[212:215], v[40:43]
	v_mfma_f32_16x16x32_bf16 v[28:31], v[178:181], v[220:223], v[28:31]
	v_mfma_f32_16x16x32_bf16 v[24:27], v[186:189], v[220:223], v[24:27]
	v_mfma_f32_16x16x32_bf16 v[12:15], v[178:181], v[228:231], v[12:15]
	v_mfma_f32_16x16x32_bf16 v[8:11], v[186:189], v[228:231], v[8:11]
	v_mfma_f32_16x16x32_bf16 v[4:7], v[178:181], v[236:239], v[4:7]
	v_mfma_f32_16x16x32_bf16 v[0:3], v[186:189], v[236:239], v[0:3]
	v_mfma_f32_16x16x32_bf16 v[44:47], v[182:185], v[216:219], v[44:47]
	v_mfma_f32_16x16x32_bf16 v[40:43], v[208:211], v[216:219], v[40:43]
	v_mfma_f32_16x16x32_bf16 v[28:31], v[182:185], v[224:227], v[28:31]
	v_mfma_f32_16x16x32_bf16 v[24:27], v[208:211], v[224:227], v[24:27]
	v_mfma_f32_16x16x32_bf16 v[12:15], v[182:185], v[232:235], v[12:15]
	v_mfma_f32_16x16x32_bf16 v[8:11], v[208:211], v[232:235], v[8:11]
	v_mfma_f32_16x16x32_bf16 v[4:7], v[182:185], v[240:243], v[4:7]
	v_mfma_f32_16x16x32_bf16 v[0:3], v[208:211], v[240:243], v[0:3]
	s_barrier
	s_add_i32 s64, s64, 2
	s_add_u32 s42, s42, 0x100
	s_addc_u32 s43, s43, 0
	s_add_u32 s22, s22, 0x100
	s_addc_u32 s30, s30, 0
	s_cmp_gt_u32 s64, 13
	s_cbranch_scc0 .LBB0_645
	v_readlane_b32 s0, v252, 26
	v_readlane_b32 s1, v252, 27
	s_and_b64 vcc, exec, s[0:1]
	v_readlane_b32 s68, v252, 11
	v_readlane_b32 s69, v252, 12
	s_cbranch_vccz .LBB0_648
	s_barrier

.LBB0_1180:
	s_add_u32 s37, s42, 0xfffc0080
	s_addc_u32 s39, s43, -1
	s_add_i32 s65, 0, 0x10000
	s_cmp_eq_u32 s64, 12
	s_cselect_b32 s63, s0, s39
	s_cselect_b32 s62, s1, s37
	v_add_u32_e32 v145, s65, v162
	s_cselect_b32 s45, s20, s30
	s_cselect_b32 s44, s21, s22
	s_add_i32 s37, 0, 0x14000
	ds_read_b128 v[146:149], v145
	ds_read_b128 v[150:153], v145 offset:1024
	ds_read_b128 v[154:157], v145 offset:2048
	ds_read_b128 v[170:173], v145 offset:3072
	v_add_u32_e32 v145, s37, v162
	ds_read_b128 v[178:181], v145
	ds_read_b128 v[182:185], v145 offset:1024
	ds_read_b128 v[186:189], v145 offset:2048
	ds_read_b128 v[208:211], v145 offset:3072
	v_lshl_add_u64 v[158:159], s[42:43], 0, v[140:141]
	s_add_i32 m0, s56, 0xc000
	ds_read_b128 v[212:215], v168
	ds_read_b128 v[216:219], v168 offset:1024
	ds_read_b128 v[220:223], v168 offset:2048
	ds_read_b128 v[224:227], v168 offset:3072
	ds_read_b128 v[228:231], v168 offset:4096
	ds_read_b128 v[232:235], v168 offset:5120
	ds_read_b128 v[236:239], v168 offset:6144
	ds_read_b128 v[240:243], v168 offset:7168
	global_load_lds_dwordx4 v[158:159], off
	v_lshl_add_u64 v[158:159], s[42:43], 0, v[142:143]
	s_add_i32 m0, s56, 0xe000
	s_nop 0
	global_load_lds_dwordx4 v[158:159], off
	s_waitcnt vmcnt(8)
	s_waitcnt lgkmcnt(0)
	s_barrier
	s_waitcnt lgkmcnt(0)
	v_mfma_f32_16x16x32_bf16 v[124:127], v[146:149], v[212:215], v[124:127]
	v_mfma_f32_16x16x32_bf16 v[120:123], v[154:157], v[212:215], v[120:123]
	v_mfma_f32_16x16x32_bf16 v[116:119], v[146:149], v[220:223], v[116:119]
	v_mfma_f32_16x16x32_bf16 v[112:115], v[154:157], v[220:223], v[112:115]
	v_mfma_f32_16x16x32_bf16 v[100:103], v[146:149], v[228:231], v[100:103]
	v_mfma_f32_16x16x32_bf16 v[96:99], v[154:157], v[228:231], v[96:99]
	v_mfma_f32_16x16x32_bf16 v[84:87], v[146:149], v[236:239], v[84:87]
	v_mfma_f32_16x16x32_bf16 v[80:83], v[154:157], v[236:239], v[80:83]
	v_mfma_f32_16x16x32_bf16 v[124:127], v[150:153], v[216:219], v[124:127]
	v_mfma_f32_16x16x32_bf16 v[120:123], v[170:173], v[216:219], v[120:123]
	v_mfma_f32_16x16x32_bf16 v[116:119], v[150:153], v[224:227], v[116:119]
	v_mfma_f32_16x16x32_bf16 v[112:115], v[170:173], v[224:227], v[112:115]
	v_mfma_f32_16x16x32_bf16 v[100:103], v[150:153], v[232:235], v[100:103]
	v_mfma_f32_16x16x32_bf16 v[96:99], v[170:173], v[232:235], v[96:99]
	v_mfma_f32_16x16x32_bf16 v[84:87], v[150:153], v[240:243], v[84:87]
	v_mfma_f32_16x16x32_bf16 v[80:83], v[170:173], v[240:243], v[80:83]
	v_mfma_f32_16x16x32_bf16 v[108:111], v[178:181], v[212:215], v[108:111]
	v_mfma_f32_16x16x32_bf16 v[104:107], v[186:189], v[212:215], v[104:107]
	v_mfma_f32_16x16x32_bf16 v[92:95], v[178:181], v[220:223], v[92:95]
	v_mfma_f32_16x16x32_bf16 v[88:91], v[186:189], v[220:223], v[88:91]
	v_mfma_f32_16x16x32_bf16 v[76:79], v[178:181], v[228:231], v[76:79]
	v_mfma_f32_16x16x32_bf16 v[72:75], v[186:189], v[228:231], v[72:75]
	v_mfma_f32_16x16x32_bf16 v[68:71], v[178:181], v[236:239], v[68:71]
	v_mfma_f32_16x16x32_bf16 v[64:67], v[186:189], v[236:239], v[64:67]
	v_mfma_f32_16x16x32_bf16 v[108:111], v[182:185], v[216:219], v[108:111]
	v_mfma_f32_16x16x32_bf16 v[104:107], v[208:211], v[216:219], v[104:107]
	v_mfma_f32_16x16x32_bf16 v[92:95], v[182:185], v[224:227], v[92:95]
	v_mfma_f32_16x16x32_bf16 v[88:91], v[208:211], v[224:227], v[88:91]
	v_mfma_f32_16x16x32_bf16 v[76:79], v[182:185], v[232:235], v[76:79]
	v_mfma_f32_16x16x32_bf16 v[72:75], v[208:211], v[232:235], v[72:75]
	v_mfma_f32_16x16x32_bf16 v[68:71], v[182:185], v[240:243], v[68:71]
	v_mfma_f32_16x16x32_bf16 v[64:67], v[208:211], v[240:243], v[64:67]
	s_barrier
	s_add_i32 s39, s65, s52
	v_lshl_add_u64 v[158:159], s[44:45], 0, v[132:133]
	s_mov_b32 m0, s39
	ds_read_b128 v[212:215], v168 offset:16384
	ds_read_b128 v[216:219], v168 offset:17408
	ds_read_b128 v[220:223], v168 offset:18432
	ds_read_b128 v[224:227], v168 offset:19456
	ds_read_b128 v[228:231], v168 offset:20480
	ds_read_b128 v[232:235], v168 offset:21504
	ds_read_b128 v[236:239], v168 offset:22528
	ds_read_b128 v[240:243], v168 offset:23552
	global_load_lds_dwordx4 v[158:159], off
	s_add_i32 m0, s39, 0x2000
	s_add_u32 s66, s44, 0x10000
	v_lshl_add_u64 v[174:175], s[44:45], 0, v[128:129]
	s_addc_u32 s67, s45, 0
	s_add_i32 s37, s37, s52
	global_load_lds_dwordx4 v[174:175], off
	v_lshl_add_u64 v[244:245], s[66:67], 0, v[132:133]
	s_mov_b32 m0, s37
	v_lshl_add_u64 v[246:247], s[62:63], 0, v[130:131]
	global_load_lds_dwordx4 v[244:245], off
	v_lshl_add_u64 v[244:245], s[66:67], 0, v[128:129]
	s_add_i32 m0, s37, 0x2000
	s_nop 0
	global_load_lds_dwordx4 v[244:245], off
	v_lshl_add_u64 v[244:245], s[62:63], 0, v[134:135]
	s_mov_b32 m0, s56
	s_nop 0
	global_load_lds_dwordx4 v[244:245], off
	s_mov_b32 m0, s57
	s_nop 0
	global_load_lds_dwordx4 v[246:247], off
	s_waitcnt vmcnt(8)
	s_waitcnt lgkmcnt(0)
	s_barrier
	s_waitcnt lgkmcnt(0)
	v_mfma_f32_16x16x32_bf16 v[60:63], v[146:149], v[212:215], v[60:63]
	v_mfma_f32_16x16x32_bf16 v[56:59], v[154:157], v[212:215], v[56:59]
	v_mfma_f32_16x16x32_bf16 v[52:55], v[146:149], v[220:223], v[52:55]
	v_mfma_f32_16x16x32_bf16 v[48:51], v[154:157], v[220:223], v[48:51]
	v_mfma_f32_16x16x32_bf16 v[36:39], v[146:149], v[228:231], v[36:39]
	v_mfma_f32_16x16x32_bf16 v[32:35], v[154:157], v[228:231], v[32:35]
	v_mfma_f32_16x16x32_bf16 v[20:23], v[146:149], v[236:239], v[20:23]
	v_mfma_f32_16x16x32_bf16 v[16:19], v[154:157], v[236:239], v[16:19]
	v_mfma_f32_16x16x32_bf16 v[60:63], v[150:153], v[216:219], v[60:63]
	v_mfma_f32_16x16x32_bf16 v[56:59], v[170:173], v[216:219], v[56:59]
	v_mfma_f32_16x16x32_bf16 v[52:55], v[150:153], v[224:227], v[52:55]
	v_mfma_f32_16x16x32_bf16 v[48:51], v[170:173], v[224:227], v[48:51]
	v_mfma_f32_16x16x32_bf16 v[36:39], v[150:153], v[232:235], v[36:39]
	v_mfma_f32_16x16x32_bf16 v[32:35], v[170:173], v[232:235], v[32:35]
	v_mfma_f32_16x16x32_bf16 v[20:23], v[150:153], v[240:243], v[20:23]
	v_mfma_f32_16x16x32_bf16 v[16:19], v[170:173], v[240:243], v[16:19]
	v_mfma_f32_16x16x32_bf16 v[44:47], v[178:181], v[212:215], v[44:47]
	v_mfma_f32_16x16x32_bf16 v[40:43], v[186:189], v[212:215], v[40:43]
	v_mfma_f32_16x16x32_bf16 v[28:31], v[178:181], v[220:223], v[28:31]
	v_mfma_f32_16x16x32_bf16 v[24:27], v[186:189], v[220:223], v[24:27]
	v_mfma_f32_16x16x32_bf16 v[12:15], v[178:181], v[228:231], v[12:15]
	v_mfma_f32_16x16x32_bf16 v[8:11], v[186:189], v[228:231], v[8:11]
	v_mfma_f32_16x16x32_bf16 v[4:7], v[178:181], v[236:239], v[4:7]
	v_mfma_f32_16x16x32_bf16 v[0:3], v[186:189], v[236:239], v[0:3]
	v_mfma_f32_16x16x32_bf16 v[44:47], v[182:185], v[216:219], v[44:47]
	v_mfma_f32_16x16x32_bf16 v[40:43], v[208:211], v[216:219], v[40:43]
	v_mfma_f32_16x16x32_bf16 v[28:31], v[182:185], v[224:227], v[28:31]
	v_mfma_f32_16x16x32_bf16 v[24:27], v[208:211], v[224:227], v[24:27]
	v_mfma_f32_16x16x32_bf16 v[12:15], v[182:185], v[232:235], v[12:15]
	v_mfma_f32_16x16x32_bf16 v[8:11], v[208:211], v[232:235], v[8:11]
	v_mfma_f32_16x16x32_bf16 v[4:7], v[182:185], v[240:243], v[4:7]
	v_mfma_f32_16x16x32_bf16 v[0:3], v[208:211], v[240:243], v[0:3]
	s_barrier
	s_add_i32 s37, 0, 0x18000
	v_add_u32_e32 v145, s37, v162
	s_add_i32 s39, 0, 0x1c000
	ds_read_b128 v[146:149], v145
	ds_read_b128 v[150:153], v145 offset:1024
	ds_read_b128 v[154:157], v145 offset:2048
	ds_read_b128 v[170:173], v145 offset:3072
	v_add_u32_e32 v145, s39, v162
	ds_read_b128 v[178:181], v145
	ds_read_b128 v[182:185], v145 offset:1024
	ds_read_b128 v[186:189], v145 offset:2048
	ds_read_b128 v[208:211], v145 offset:3072
	s_add_u32 s62, s62, 0x40000
	s_addc_u32 s63, s63, 0
	s_mov_b32 m0, s54
	v_lshl_add_u64 v[248:249], s[62:63], 0, v[134:135]
	ds_read_b128 v[212:215], v168 offset:32768
	ds_read_b128 v[216:219], v168 offset:33792
	ds_read_b128 v[220:223], v168 offset:34816
	ds_read_b128 v[224:227], v168 offset:35840
	ds_read_b128 v[228:231], v168 offset:36864
	ds_read_b128 v[232:235], v168 offset:37888
	ds_read_b128 v[236:239], v168 offset:38912
	ds_read_b128 v[240:243], v168 offset:39936
	global_load_lds_dwordx4 v[248:249], off
	v_lshl_add_u64 v[248:249], s[62:63], 0, v[130:131]
	s_mov_b32 m0, s55
	s_nop 0
	global_load_lds_dwordx4 v[248:249], off
	s_waitcnt vmcnt(8)
	s_waitcnt lgkmcnt(0)
	s_barrier
	s_waitcnt lgkmcnt(0)
	v_mfma_f32_16x16x32_bf16 v[124:127], v[146:149], v[212:215], v[124:127]
	v_mfma_f32_16x16x32_bf16 v[120:123], v[154:157], v[212:215], v[120:123]
	v_mfma_f32_16x16x32_bf16 v[116:119], v[146:149], v[220:223], v[116:119]
	v_mfma_f32_16x16x32_bf16 v[112:115], v[154:157], v[220:223], v[112:115]
	v_mfma_f32_16x16x32_bf16 v[100:103], v[146:149], v[228:231], v[100:103]
	v_mfma_f32_16x16x32_bf16 v[96:99], v[154:157], v[228:231], v[96:99]
	v_mfma_f32_16x16x32_bf16 v[84:87], v[146:149], v[236:239], v[84:87]
	v_mfma_f32_16x16x32_bf16 v[80:83], v[154:157], v[236:239], v[80:83]
	v_mfma_f32_16x16x32_bf16 v[124:127], v[150:153], v[216:219], v[124:127]
	v_mfma_f32_16x16x32_bf16 v[120:123], v[170:173], v[216:219], v[120:123]
	v_mfma_f32_16x16x32_bf16 v[116:119], v[150:153], v[224:227], v[116:119]
	v_mfma_f32_16x16x32_bf16 v[112:115], v[170:173], v[224:227], v[112:115]
	v_mfma_f32_16x16x32_bf16 v[100:103], v[150:153], v[232:235], v[100:103]
	v_mfma_f32_16x16x32_bf16 v[96:99], v[170:173], v[232:235], v[96:99]
	v_mfma_f32_16x16x32_bf16 v[84:87], v[150:153], v[240:243], v[84:87]
	v_mfma_f32_16x16x32_bf16 v[80:83], v[170:173], v[240:243], v[80:83]
	v_mfma_f32_16x16x32_bf16 v[108:111], v[178:181], v[212:215], v[108:111]
	v_mfma_f32_16x16x32_bf16 v[104:107], v[186:189], v[212:215], v[104:107]
	v_mfma_f32_16x16x32_bf16 v[92:95], v[178:181], v[220:223], v[92:95]
	v_mfma_f32_16x16x32_bf16 v[88:91], v[186:189], v[220:223], v[88:91]
	v_mfma_f32_16x16x32_bf16 v[76:79], v[178:181], v[228:231], v[76:79]
	v_mfma_f32_16x16x32_bf16 v[72:75], v[186:189], v[228:231], v[72:75]
	v_mfma_f32_16x16x32_bf16 v[68:71], v[178:181], v[236:239], v[68:71]
	v_mfma_f32_16x16x32_bf16 v[64:67], v[186:189], v[236:239], v[64:67]
	v_mfma_f32_16x16x32_bf16 v[108:111], v[182:185], v[216:219], v[108:111]
	v_mfma_f32_16x16x32_bf16 v[104:107], v[208:211], v[216:219], v[104:107]
	v_mfma_f32_16x16x32_bf16 v[92:95], v[182:185], v[224:227], v[92:95]
	v_mfma_f32_16x16x32_bf16 v[88:91], v[208:211], v[224:227], v[88:91]
	v_mfma_f32_16x16x32_bf16 v[76:79], v[182:185], v[232:235], v[76:79]
	v_mfma_f32_16x16x32_bf16 v[72:75], v[208:211], v[232:235], v[72:75]
	v_mfma_f32_16x16x32_bf16 v[68:71], v[182:185], v[240:243], v[68:71]
	v_mfma_f32_16x16x32_bf16 v[64:67], v[208:211], v[240:243], v[64:67]
	s_barrier
	s_add_i32 s37, s37, s52
	v_lshl_add_u64 v[158:159], v[158:159], 0, s[26:27]
	s_mov_b32 m0, s37
	ds_read_b128 v[212:215], v168 offset:49152
	ds_read_b128 v[216:219], v168 offset:50176
	ds_read_b128 v[220:223], v168 offset:51200
	ds_read_b128 v[224:227], v168 offset:52224
	ds_read_b128 v[228:231], v168 offset:53248
	ds_read_b128 v[232:235], v168 offset:54272
	ds_read_b128 v[236:239], v168 offset:55296
	ds_read_b128 v[240:243], v168 offset:56320
	global_load_lds_dwordx4 v[158:159], off
	s_add_i32 m0, s37, 0x2000
	s_add_u32 s44, s44, 0x10080
	v_lshl_add_u64 v[158:159], v[174:175], 0, s[26:27]
	s_addc_u32 s45, s45, 0
	s_add_i32 s37, s39, s52
	global_load_lds_dwordx4 v[158:159], off
	v_lshl_add_u64 v[158:159], s[44:45], 0, v[132:133]
	s_mov_b32 m0, s37
	s_nop 0
	global_load_lds_dwordx4 v[158:159], off
	v_lshl_add_u64 v[158:159], s[44:45], 0, v[128:129]
	s_add_i32 m0, s37, 0x2000
	s_nop 0
	global_load_lds_dwordx4 v[158:159], off
	v_lshl_add_u64 v[158:159], v[244:245], 0, s[26:27]
	s_mov_b32 m0, s35
	s_nop 0
	global_load_lds_dwordx4 v[158:159], off
	v_lshl_add_u64 v[158:159], v[246:247], 0, s[26:27]
	s_mov_b32 m0, s53
	s_nop 0
	global_load_lds_dwordx4 v[158:159], off
	s_waitcnt vmcnt(8)
	s_waitcnt lgkmcnt(0)
	s_barrier
	s_waitcnt lgkmcnt(0)
	v_mfma_f32_16x16x32_bf16 v[60:63], v[146:149], v[212:215], v[60:63]
	v_mfma_f32_16x16x32_bf16 v[56:59], v[154:157], v[212:215], v[56:59]
	v_mfma_f32_16x16x32_bf16 v[52:55], v[146:149], v[220:223], v[52:55]
	v_mfma_f32_16x16x32_bf16 v[48:51], v[154:157], v[220:223], v[48:51]
	v_mfma_f32_16x16x32_bf16 v[36:39], v[146:149], v[228:231], v[36:39]
	v_mfma_f32_16x16x32_bf16 v[32:35], v[154:157], v[228:231], v[32:35]
	v_mfma_f32_16x16x32_bf16 v[20:23], v[146:149], v[236:239], v[20:23]
	v_mfma_f32_16x16x32_bf16 v[16:19], v[154:157], v[236:239], v[16:19]
	v_mfma_f32_16x16x32_bf16 v[60:63], v[150:153], v[216:219], v[60:63]
	v_mfma_f32_16x16x32_bf16 v[56:59], v[170:173], v[216:219], v[56:59]
	v_mfma_f32_16x16x32_bf16 v[52:55], v[150:153], v[224:227], v[52:55]
	v_mfma_f32_16x16x32_bf16 v[48:51], v[170:173], v[224:227], v[48:51]
	v_mfma_f32_16x16x32_bf16 v[36:39], v[150:153], v[232:235], v[36:39]
	v_mfma_f32_16x16x32_bf16 v[32:35], v[170:173], v[232:235], v[32:35]
	v_mfma_f32_16x16x32_bf16 v[20:23], v[150:153], v[240:243], v[20:23]
	v_mfma_f32_16x16x32_bf16 v[16:19], v[170:173], v[240:243], v[16:19]
	v_mfma_f32_16x16x32_bf16 v[44:47], v[178:181], v[212:215], v[44:47]
	v_mfma_f32_16x16x32_bf16 v[40:43], v[186:189], v[212:215], v[40:43]
	v_mfma_f32_16x16x32_bf16 v[28:31], v[178:181], v[220:223], v[28:31]
	v_mfma_f32_16x16x32_bf16 v[24:27], v[186:189], v[220:223], v[24:27]
	v_mfma_f32_16x16x32_bf16 v[12:15], v[178:181], v[228:231], v[12:15]
	v_mfma_f32_16x16x32_bf16 v[8:11], v[186:189], v[228:231], v[8:11]
	v_mfma_f32_16x16x32_bf16 v[4:7], v[178:181], v[236:239], v[4:7]
	v_mfma_f32_16x16x32_bf16 v[0:3], v[186:189], v[236:239], v[0:3]
	v_mfma_f32_16x16x32_bf16 v[44:47], v[182:185], v[216:219], v[44:47]
	v_mfma_f32_16x16x32_bf16 v[40:43], v[208:211], v[216:219], v[40:43]
	v_mfma_f32_16x16x32_bf16 v[28:31], v[182:185], v[224:227], v[28:31]
	v_mfma_f32_16x16x32_bf16 v[24:27], v[208:211], v[224:227], v[24:27]
	v_mfma_f32_16x16x32_bf16 v[12:15], v[182:185], v[232:235], v[12:15]
	v_mfma_f32_16x16x32_bf16 v[8:11], v[208:211], v[232:235], v[8:11]
	v_mfma_f32_16x16x32_bf16 v[4:7], v[182:185], v[240:243], v[4:7]
	v_mfma_f32_16x16x32_bf16 v[0:3], v[208:211], v[240:243], v[0:3]
	s_barrier
	s_add_i32 s64, s64, 2
	s_add_u32 s42, s42, 0x100
	s_addc_u32 s43, s43, 0
	s_add_u32 s22, s22, 0x100
	s_addc_u32 s30, s30, 0
	s_cmp_gt_u32 s64, 13
	s_cbranch_scc0 .LBB0_1180
	v_readlane_b32 s0, v252, 26
	v_readlane_b32 s1, v252, 27
	s_and_b64 vcc, exec, s[0:1]
	v_readlane_b32 s68, v252, 11
	v_readlane_b32 s69, v252, 12
	s_cbranch_vccz .LBB0_1183
	s_barrier

.LBB0_1251:
	s_add_u32 s56, s54, 0x100
	s_addc_u32 s57, s55, 0
	s_add_i32 s34, 0, 0x10000
	s_cmp_eq_u32 s49, 40
	s_cselect_b32 s61, s20, s57
	s_cselect_b32 s60, s21, s56
	s_cselect_b32 s59, s70, s48
	s_cselect_b32 s58, vcc_lo, vcc_hi
	s_add_i32 s37, 0, 0x14000
	v_add_u32_e32 v168, s34, v178
	v_add_u32_e32 v188, s37, v178
	ds_read_b128 v[128:131], v168
	ds_read_b128 v[132:135], v168 offset:1024
	ds_read_b128 v[164:167], v168 offset:2048
	ds_read_b128 v[168:171], v168 offset:3072
	ds_read_b128 v[172:175], v188
	ds_read_b128 v[180:183], v188 offset:1024
	ds_read_b128 v[184:187], v188 offset:2048
	ds_read_b128 v[208:211], v188 offset:3072
	v_lshl_add_u64 v[188:189], s[54:55], 0, v[160:161]
	s_add_i32 m0, s62, 0xc000
	ds_read_b128 v[212:215], v179
	ds_read_b128 v[216:219], v179 offset:1024
	ds_read_b128 v[220:223], v179 offset:2048
	ds_read_b128 v[224:227], v179 offset:3072
	ds_read_b128 v[228:231], v179 offset:4096
	ds_read_b128 v[232:235], v179 offset:5120
	ds_read_b128 v[236:239], v179 offset:6144
	ds_read_b128 v[240:243], v179 offset:7168
	global_load_lds_dwordx4 v[188:189], off
	v_lshl_add_u64 v[188:189], s[54:55], 0, v[162:163]
	s_add_i32 m0, s62, 0xe000
	s_nop 0
	global_load_lds_dwordx4 v[188:189], off
	s_waitcnt vmcnt(8)
	s_waitcnt lgkmcnt(0)
	s_barrier
	s_waitcnt lgkmcnt(0)
	v_mfma_f32_16x16x32_bf16 v[124:127], v[128:131], v[212:215], v[124:127]
	v_mfma_f32_16x16x32_bf16 v[120:123], v[164:167], v[212:215], v[120:123]
	v_mfma_f32_16x16x32_bf16 v[116:119], v[128:131], v[220:223], v[116:119]
	v_mfma_f32_16x16x32_bf16 v[112:115], v[164:167], v[220:223], v[112:115]
	v_mfma_f32_16x16x32_bf16 v[108:111], v[128:131], v[228:231], v[108:111]
	v_mfma_f32_16x16x32_bf16 v[104:107], v[164:167], v[228:231], v[104:107]
	v_mfma_f32_16x16x32_bf16 v[100:103], v[128:131], v[236:239], v[100:103]
	v_mfma_f32_16x16x32_bf16 v[96:99], v[164:167], v[236:239], v[96:99]
	v_mfma_f32_16x16x32_bf16 v[124:127], v[132:135], v[216:219], v[124:127]
	v_mfma_f32_16x16x32_bf16 v[120:123], v[168:171], v[216:219], v[120:123]
	v_mfma_f32_16x16x32_bf16 v[116:119], v[132:135], v[224:227], v[116:119]
	v_mfma_f32_16x16x32_bf16 v[112:115], v[168:171], v[224:227], v[112:115]
	v_mfma_f32_16x16x32_bf16 v[108:111], v[132:135], v[232:235], v[108:111]
	v_mfma_f32_16x16x32_bf16 v[104:107], v[168:171], v[232:235], v[104:107]
	v_mfma_f32_16x16x32_bf16 v[100:103], v[132:135], v[240:243], v[100:103]
	v_mfma_f32_16x16x32_bf16 v[96:99], v[168:171], v[240:243], v[96:99]
	v_mfma_f32_16x16x32_bf16 v[60:63], v[172:175], v[212:215], v[60:63]
	v_mfma_f32_16x16x32_bf16 v[56:59], v[184:187], v[212:215], v[56:59]
	v_mfma_f32_16x16x32_bf16 v[52:55], v[172:175], v[220:223], v[52:55]
	v_mfma_f32_16x16x32_bf16 v[48:51], v[184:187], v[220:223], v[48:51]
	v_mfma_f32_16x16x32_bf16 v[44:47], v[172:175], v[228:231], v[44:47]
	v_mfma_f32_16x16x32_bf16 v[40:43], v[184:187], v[228:231], v[40:43]
	v_mfma_f32_16x16x32_bf16 v[36:39], v[172:175], v[236:239], v[36:39]
	v_mfma_f32_16x16x32_bf16 v[32:35], v[184:187], v[236:239], v[32:35]
	v_mfma_f32_16x16x32_bf16 v[60:63], v[180:183], v[216:219], v[60:63]
	v_mfma_f32_16x16x32_bf16 v[56:59], v[208:211], v[216:219], v[56:59]
	v_mfma_f32_16x16x32_bf16 v[52:55], v[180:183], v[224:227], v[52:55]
	v_mfma_f32_16x16x32_bf16 v[48:51], v[208:211], v[224:227], v[48:51]
	v_mfma_f32_16x16x32_bf16 v[44:47], v[180:183], v[232:235], v[44:47]
	v_mfma_f32_16x16x32_bf16 v[40:43], v[208:211], v[232:235], v[40:43]
	v_mfma_f32_16x16x32_bf16 v[36:39], v[180:183], v[240:243], v[36:39]
	v_mfma_f32_16x16x32_bf16 v[32:35], v[208:211], v[240:243], v[32:35]
	s_barrier
	s_add_i32 s34, s34, s35
	v_lshl_add_u64 v[188:189], s[58:59], 0, v[140:141]
	s_mov_b32 m0, s34
	ds_read_b128 v[212:215], v179 offset:16384
	ds_read_b128 v[216:219], v179 offset:17408
	ds_read_b128 v[220:223], v179 offset:18432
	ds_read_b128 v[224:227], v179 offset:19456
	ds_read_b128 v[228:231], v179 offset:20480
	ds_read_b128 v[232:235], v179 offset:21504
	ds_read_b128 v[236:239], v179 offset:22528
	ds_read_b128 v[240:243], v179 offset:23552
	global_load_lds_dwordx4 v[188:189], off
	s_add_i32 m0, s34, 0x2000
	s_add_u32 s54, s58, 0x2c000
	v_lshl_add_u64 v[244:245], s[58:59], 0, v[136:137]
	s_addc_u32 s55, s59, 0
	s_add_i32 s34, s37, s35
	global_load_lds_dwordx4 v[244:245], off
	v_lshl_add_u64 v[246:247], s[54:55], 0, v[140:141]
	s_mov_b32 m0, s34
	v_lshl_add_u64 v[248:249], s[60:61], 0, v[138:139]
	global_load_lds_dwordx4 v[246:247], off
	v_lshl_add_u64 v[246:247], s[54:55], 0, v[136:137]
	s_add_i32 m0, s34, 0x2000
	s_nop 0
	global_load_lds_dwordx4 v[246:247], off
	v_lshl_add_u64 v[246:247], s[60:61], 0, v[142:143]
	s_mov_b32 m0, s62
	s_nop 0
	global_load_lds_dwordx4 v[246:247], off
	s_mov_b32 m0, s63
	s_nop 0
	global_load_lds_dwordx4 v[248:249], off
	s_waitcnt vmcnt(8)
	s_waitcnt lgkmcnt(0)
	s_barrier
	s_waitcnt lgkmcnt(0)
	v_mfma_f32_16x16x32_bf16 v[92:95], v[128:131], v[212:215], v[92:95]
	v_mfma_f32_16x16x32_bf16 v[88:91], v[164:167], v[212:215], v[88:91]
	v_mfma_f32_16x16x32_bf16 v[84:87], v[128:131], v[220:223], v[84:87]
	v_mfma_f32_16x16x32_bf16 v[80:83], v[164:167], v[220:223], v[80:83]
	v_mfma_f32_16x16x32_bf16 v[76:79], v[128:131], v[228:231], v[76:79]
	v_mfma_f32_16x16x32_bf16 v[72:75], v[164:167], v[228:231], v[72:75]
	v_mfma_f32_16x16x32_bf16 v[68:71], v[128:131], v[236:239], v[68:71]
	v_mfma_f32_16x16x32_bf16 v[64:67], v[164:167], v[236:239], v[64:67]
	v_mfma_f32_16x16x32_bf16 v[92:95], v[132:135], v[216:219], v[92:95]
	v_mfma_f32_16x16x32_bf16 v[88:91], v[168:171], v[216:219], v[88:91]
	v_mfma_f32_16x16x32_bf16 v[84:87], v[132:135], v[224:227], v[84:87]
	v_mfma_f32_16x16x32_bf16 v[80:83], v[168:171], v[224:227], v[80:83]
	v_mfma_f32_16x16x32_bf16 v[76:79], v[132:135], v[232:235], v[76:79]
	v_mfma_f32_16x16x32_bf16 v[72:75], v[168:171], v[232:235], v[72:75]
	v_mfma_f32_16x16x32_bf16 v[68:71], v[132:135], v[240:243], v[68:71]
	v_mfma_f32_16x16x32_bf16 v[64:67], v[168:171], v[240:243], v[64:67]
	v_mfma_f32_16x16x32_bf16 v[28:31], v[172:175], v[212:215], v[28:31]
	v_mfma_f32_16x16x32_bf16 v[24:27], v[184:187], v[212:215], v[24:27]
	v_mfma_f32_16x16x32_bf16 v[20:23], v[172:175], v[220:223], v[20:23]
	v_mfma_f32_16x16x32_bf16 v[16:19], v[184:187], v[220:223], v[16:19]
	v_mfma_f32_16x16x32_bf16 v[12:15], v[172:175], v[228:231], v[12:15]
	v_mfma_f32_16x16x32_bf16 v[8:11], v[184:187], v[228:231], v[8:11]
	v_mfma_f32_16x16x32_bf16 v[4:7], v[172:175], v[236:239], v[4:7]
	v_mfma_f32_16x16x32_bf16 v[0:3], v[184:187], v[236:239], v[0:3]
	v_mfma_f32_16x16x32_bf16 v[28:31], v[180:183], v[216:219], v[28:31]
	v_mfma_f32_16x16x32_bf16 v[24:27], v[208:211], v[216:219], v[24:27]
	v_mfma_f32_16x16x32_bf16 v[20:23], v[180:183], v[224:227], v[20:23]
	v_mfma_f32_16x16x32_bf16 v[16:19], v[208:211], v[224:227], v[16:19]
	v_mfma_f32_16x16x32_bf16 v[12:15], v[180:183], v[232:235], v[12:15]
	v_mfma_f32_16x16x32_bf16 v[8:11], v[208:211], v[232:235], v[8:11]
	v_mfma_f32_16x16x32_bf16 v[4:7], v[180:183], v[240:243], v[4:7]
	v_mfma_f32_16x16x32_bf16 v[0:3], v[208:211], v[240:243], v[0:3]
	s_barrier
	s_add_i32 s34, 0, 0x18000
	s_add_i32 s37, 0, 0x1c000
	v_add_u32_e32 v168, s34, v178
	v_add_u32_e32 v207, s37, v178
	ds_read_b128 v[128:131], v168
	ds_read_b128 v[132:135], v168 offset:1024
	ds_read_b128 v[164:167], v168 offset:2048
	ds_read_b128 v[168:171], v168 offset:3072
	ds_read_b128 v[172:175], v207
	ds_read_b128 v[180:183], v207 offset:1024
	ds_read_b128 v[184:187], v207 offset:2048
	ds_read_b128 v[208:211], v207 offset:3072
	s_add_u32 s54, s60, 0xb0000
	s_addc_u32 s55, s61, 0
	s_mov_b32 m0, s64
	v_lshl_add_u64 v[250:251], s[54:55], 0, v[142:143]
	ds_read_b128 v[212:215], v179 offset:32768
	ds_read_b128 v[216:219], v179 offset:33792
	ds_read_b128 v[220:223], v179 offset:34816
	ds_read_b128 v[224:227], v179 offset:35840
	ds_read_b128 v[228:231], v179 offset:36864
	ds_read_b128 v[232:235], v179 offset:37888
	ds_read_b128 v[236:239], v179 offset:38912
	ds_read_b128 v[240:243], v179 offset:39936
	global_load_lds_dwordx4 v[250:251], off
	v_lshl_add_u64 v[250:251], s[54:55], 0, v[138:139]
	s_mov_b32 m0, s65
	s_nop 0
	global_load_lds_dwordx4 v[250:251], off
	s_waitcnt vmcnt(8)
	s_waitcnt lgkmcnt(0)
	s_barrier
	s_waitcnt lgkmcnt(0)
	v_mfma_f32_16x16x32_bf16 v[124:127], v[128:131], v[212:215], v[124:127]
	v_mfma_f32_16x16x32_bf16 v[120:123], v[164:167], v[212:215], v[120:123]
	v_mfma_f32_16x16x32_bf16 v[116:119], v[128:131], v[220:223], v[116:119]
	v_mfma_f32_16x16x32_bf16 v[112:115], v[164:167], v[220:223], v[112:115]
	v_mfma_f32_16x16x32_bf16 v[108:111], v[128:131], v[228:231], v[108:111]
	v_mfma_f32_16x16x32_bf16 v[104:107], v[164:167], v[228:231], v[104:107]
	v_mfma_f32_16x16x32_bf16 v[100:103], v[128:131], v[236:239], v[100:103]
	v_mfma_f32_16x16x32_bf16 v[96:99], v[164:167], v[236:239], v[96:99]
	v_mfma_f32_16x16x32_bf16 v[124:127], v[132:135], v[216:219], v[124:127]
	v_mfma_f32_16x16x32_bf16 v[120:123], v[168:171], v[216:219], v[120:123]
	v_mfma_f32_16x16x32_bf16 v[116:119], v[132:135], v[224:227], v[116:119]
	v_mfma_f32_16x16x32_bf16 v[112:115], v[168:171], v[224:227], v[112:115]
	v_mfma_f32_16x16x32_bf16 v[108:111], v[132:135], v[232:235], v[108:111]
	v_mfma_f32_16x16x32_bf16 v[104:107], v[168:171], v[232:235], v[104:107]
	v_mfma_f32_16x16x32_bf16 v[100:103], v[132:135], v[240:243], v[100:103]
	v_mfma_f32_16x16x32_bf16 v[96:99], v[168:171], v[240:243], v[96:99]
	v_mfma_f32_16x16x32_bf16 v[60:63], v[172:175], v[212:215], v[60:63]
	v_mfma_f32_16x16x32_bf16 v[56:59], v[184:187], v[212:215], v[56:59]
	v_mfma_f32_16x16x32_bf16 v[52:55], v[172:175], v[220:223], v[52:55]
	v_mfma_f32_16x16x32_bf16 v[48:51], v[184:187], v[220:223], v[48:51]
	v_mfma_f32_16x16x32_bf16 v[44:47], v[172:175], v[228:231], v[44:47]
	v_mfma_f32_16x16x32_bf16 v[40:43], v[184:187], v[228:231], v[40:43]
	v_mfma_f32_16x16x32_bf16 v[36:39], v[172:175], v[236:239], v[36:39]
	v_mfma_f32_16x16x32_bf16 v[32:35], v[184:187], v[236:239], v[32:35]
	v_mfma_f32_16x16x32_bf16 v[60:63], v[180:183], v[216:219], v[60:63]
	v_mfma_f32_16x16x32_bf16 v[56:59], v[208:211], v[216:219], v[56:59]
	v_mfma_f32_16x16x32_bf16 v[52:55], v[180:183], v[224:227], v[52:55]
	v_mfma_f32_16x16x32_bf16 v[48:51], v[208:211], v[224:227], v[48:51]
	v_mfma_f32_16x16x32_bf16 v[44:47], v[180:183], v[232:235], v[44:47]
	v_mfma_f32_16x16x32_bf16 v[40:43], v[208:211], v[232:235], v[40:43]
	v_mfma_f32_16x16x32_bf16 v[36:39], v[180:183], v[240:243], v[36:39]
	v_mfma_f32_16x16x32_bf16 v[32:35], v[208:211], v[240:243], v[32:35]
	s_barrier
	s_add_i32 s34, s34, s35
	v_lshl_add_u64 v[188:189], v[188:189], 0, s[26:27]
	s_mov_b32 m0, s34
	ds_read_b128 v[212:215], v179 offset:49152
	ds_read_b128 v[216:219], v179 offset:50176
	ds_read_b128 v[220:223], v179 offset:51200
	ds_read_b128 v[224:227], v179 offset:52224
	ds_read_b128 v[228:231], v179 offset:53248
	ds_read_b128 v[232:235], v179 offset:54272
	ds_read_b128 v[236:239], v179 offset:55296
	ds_read_b128 v[240:243], v179 offset:56320
	global_load_lds_dwordx4 v[188:189], off
	s_add_i32 m0, s34, 0x2000
	s_add_u32 s54, s58, 0x2c080
	v_lshl_add_u64 v[188:189], v[244:245], 0, s[26:27]
	s_addc_u32 s55, s59, 0
	s_add_i32 s34, s37, s35
	global_load_lds_dwordx4 v[188:189], off
	v_lshl_add_u64 v[188:189], s[54:55], 0, v[140:141]
	s_mov_b32 m0, s34
	s_nop 0
	global_load_lds_dwordx4 v[188:189], off
	v_lshl_add_u64 v[188:189], s[54:55], 0, v[136:137]
	s_add_i32 m0, s34, 0x2000
	s_nop 0
	global_load_lds_dwordx4 v[188:189], off
	v_lshl_add_u64 v[188:189], v[246:247], 0, s[26:27]
	s_mov_b32 m0, s66
	s_nop 0
	global_load_lds_dwordx4 v[188:189], off
	v_lshl_add_u64 v[188:189], v[248:249], 0, s[26:27]
	s_mov_b32 m0, s67
	s_nop 0
	global_load_lds_dwordx4 v[188:189], off
	s_waitcnt vmcnt(8)
	s_waitcnt lgkmcnt(0)
	s_barrier
	s_waitcnt lgkmcnt(0)
	v_mfma_f32_16x16x32_bf16 v[92:95], v[128:131], v[212:215], v[92:95]
	v_mfma_f32_16x16x32_bf16 v[88:91], v[164:167], v[212:215], v[88:91]
	v_mfma_f32_16x16x32_bf16 v[84:87], v[128:131], v[220:223], v[84:87]
	v_mfma_f32_16x16x32_bf16 v[80:83], v[164:167], v[220:223], v[80:83]
	v_mfma_f32_16x16x32_bf16 v[76:79], v[128:131], v[228:231], v[76:79]
	v_mfma_f32_16x16x32_bf16 v[72:75], v[164:167], v[228:231], v[72:75]
	v_mfma_f32_16x16x32_bf16 v[68:71], v[128:131], v[236:239], v[68:71]
	v_mfma_f32_16x16x32_bf16 v[64:67], v[164:167], v[236:239], v[64:67]
	v_mfma_f32_16x16x32_bf16 v[92:95], v[132:135], v[216:219], v[92:95]
	v_mfma_f32_16x16x32_bf16 v[88:91], v[168:171], v[216:219], v[88:91]
	v_mfma_f32_16x16x32_bf16 v[84:87], v[132:135], v[224:227], v[84:87]
	v_mfma_f32_16x16x32_bf16 v[80:83], v[168:171], v[224:227], v[80:83]
	v_mfma_f32_16x16x32_bf16 v[76:79], v[132:135], v[232:235], v[76:79]
	v_mfma_f32_16x16x32_bf16 v[72:75], v[168:171], v[232:235], v[72:75]
	v_mfma_f32_16x16x32_bf16 v[68:71], v[132:135], v[240:243], v[68:71]
	v_mfma_f32_16x16x32_bf16 v[64:67], v[168:171], v[240:243], v[64:67]
	v_mfma_f32_16x16x32_bf16 v[28:31], v[172:175], v[212:215], v[28:31]
	v_mfma_f32_16x16x32_bf16 v[24:27], v[184:187], v[212:215], v[24:27]
	v_mfma_f32_16x16x32_bf16 v[20:23], v[172:175], v[220:223], v[20:23]
	v_mfma_f32_16x16x32_bf16 v[16:19], v[184:187], v[220:223], v[16:19]
	v_mfma_f32_16x16x32_bf16 v[12:15], v[172:175], v[228:231], v[12:15]
	v_mfma_f32_16x16x32_bf16 v[8:11], v[184:187], v[228:231], v[8:11]
	v_mfma_f32_16x16x32_bf16 v[4:7], v[172:175], v[236:239], v[4:7]
	v_mfma_f32_16x16x32_bf16 v[0:3], v[184:187], v[236:239], v[0:3]
	v_mfma_f32_16x16x32_bf16 v[28:31], v[180:183], v[216:219], v[28:31]
	v_mfma_f32_16x16x32_bf16 v[24:27], v[208:211], v[216:219], v[24:27]
	v_mfma_f32_16x16x32_bf16 v[20:23], v[180:183], v[224:227], v[20:23]
	v_mfma_f32_16x16x32_bf16 v[16:19], v[208:211], v[224:227], v[16:19]
	v_mfma_f32_16x16x32_bf16 v[12:15], v[180:183], v[232:235], v[12:15]
	v_mfma_f32_16x16x32_bf16 v[8:11], v[208:211], v[232:235], v[8:11]
	v_mfma_f32_16x16x32_bf16 v[4:7], v[180:183], v[240:243], v[4:7]
	v_mfma_f32_16x16x32_bf16 v[0:3], v[208:211], v[240:243], v[0:3]
	s_barrier
	s_add_i32 s49, s49, 2
	s_add_u32 vcc_hi, vcc_hi, 0x100
	s_addc_u32 s48, s48, 0
	s_cmp_gt_u32 s49, 41
	s_mov_b64 s[54:55], s[56:57]
	s_cbranch_scc0 .LBB0_1251
	v_readlane_b32 s4, v252, 28
	v_readlane_b32 s5, v252, 29
	s_and_b64 vcc, exec, s[4:5]
	s_cbranch_vccz .LBB0_1254
	s_barrier
